# v30 with the per-segment s_setprio toggles removed from the attention tile loops
# baseline (speedup 1.0000x reference)
.Lskip_v2_0:
.LBB0_625:
	s_sub_i32 s73, s18, 63
	s_cmp_gt_i32 s73, s27
	s_cbranch_scc1 .LBB0_638
	s_bitcmp1_b32 s72, 0
	s_cselect_b32 s72, 0x2400, 0
	v_add_u32_e32 v32, s72, v188
	ds_read_b128 v[214:217], v32
	ds_read_b128 v[218:221], v32 offset:4608
	ds_read_b128 v[222:225], v32 offset:32
	ds_read_b128 v[226:229], v32 offset:4640
	ds_read_b128 v[230:233], v32 offset:64
	ds_read_b128 v[234:237], v32 offset:4672
	ds_read_b128 v[238:241], v32 offset:96
	ds_read_b128 v[244:247], v32 offset:4704
	s_waitcnt lgkmcnt(7)
	v_mfma_f32_32x32x16_bf16 v[114:129], v[214:217], v[146:149], v[98:113]
	s_waitcnt lgkmcnt(6)
	v_mfma_f32_32x32x16_bf16 v[130:145], v[218:221], v[146:149], v[98:113]
	s_waitcnt lgkmcnt(5)
	v_mfma_f32_32x32x16_bf16 v[114:129], v[222:225], v[150:153], v[114:129]
	s_waitcnt lgkmcnt(4)
	v_mfma_f32_32x32x16_bf16 v[130:145], v[226:229], v[150:153], v[130:145]
	s_waitcnt lgkmcnt(3)
	v_mfma_f32_32x32x16_bf16 v[114:129], v[230:233], v[154:157], v[114:129]
	s_waitcnt lgkmcnt(2)
	v_mfma_f32_32x32x16_bf16 v[130:145], v[234:237], v[154:157], v[130:145]
	s_waitcnt lgkmcnt(1)
	v_mfma_f32_32x32x16_bf16 v[114:129], v[238:241], v[158:161], v[114:129]
	s_waitcnt lgkmcnt(0)
	v_mfma_f32_32x32x16_bf16 v[130:145], v[244:247], v[158:161], v[130:145]
	s_cmp_le_i32 s18, s76
	s_cbranch_scc1 .LBB0_628
	v_add_u32_e32 v32, s18, v190
	v_subrev_u32_e32 v200, 31, v32
	v_subrev_u32_e32 v198, 63, v32
	v_cmp_le_i32_e32 vcc, v200, v166
	s_nop 4
	v_cndmask_b32_e32 v130, v208, v130, vcc
	v_cmp_lt_i32_e32 vcc, v198, v166
	s_nop 1
	v_cndmask_b32_e32 v115, v208, v115, vcc
	v_cmp_le_i32_e32 vcc, v198, v166
	v_subrev_u32_e32 v198, 30, v32
	s_nop 0
	v_cndmask_b32_e32 v114, v208, v114, vcc
	v_cmp_le_i32_e32 vcc, v198, v166
	v_subrev_u32_e32 v198, 61, v32
	s_nop 0
	v_cndmask_b32_e32 v131, v208, v131, vcc
	v_cmp_le_i32_e32 vcc, v198, v166
	v_subrev_u32_e32 v198, 29, v32
	s_nop 0
	v_cndmask_b32_e32 v116, v208, v116, vcc
	v_cmp_le_i32_e32 vcc, v198, v166
	v_subrev_u32_e32 v198, 60, v32
	s_nop 0
	v_cndmask_b32_e32 v132, v208, v132, vcc
	v_cmp_le_i32_e32 vcc, v198, v166
	v_subrev_u32_e32 v198, 28, v32
	s_nop 0
	v_cndmask_b32_e32 v117, v208, v117, vcc
	v_cmp_le_i32_e32 vcc, v198, v166
	v_subrev_u32_e32 v198, 55, v32
	s_nop 0
	v_cndmask_b32_e32 v133, v208, v133, vcc
	v_cmp_le_i32_e32 vcc, v198, v166
	v_subrev_u32_e32 v198, 23, v32
	s_nop 0
	v_cndmask_b32_e32 v118, v208, v118, vcc
	v_cmp_le_i32_e32 vcc, v198, v166
	v_subrev_u32_e32 v198, 54, v32
	s_nop 0
	v_cndmask_b32_e32 v134, v208, v134, vcc
	v_cmp_le_i32_e32 vcc, v198, v166
	v_subrev_u32_e32 v198, 22, v32
	s_nop 0
	v_cndmask_b32_e32 v119, v208, v119, vcc
	v_cmp_le_i32_e32 vcc, v198, v166
	v_subrev_u32_e32 v198, 53, v32
	s_nop 0
	v_cndmask_b32_e32 v135, v208, v135, vcc
	v_cmp_le_i32_e32 vcc, v198, v166
	v_subrev_u32_e32 v198, 21, v32
	s_nop 0
	v_cndmask_b32_e32 v120, v208, v120, vcc
	v_cmp_le_i32_e32 vcc, v198, v166
	v_subrev_u32_e32 v198, 52, v32
	s_nop 0
	v_cndmask_b32_e32 v136, v208, v136, vcc
	v_cmp_le_i32_e32 vcc, v198, v166
	v_subrev_u32_e32 v198, 20, v32
	s_nop 0
	v_cndmask_b32_e32 v121, v208, v121, vcc
	v_cmp_le_i32_e32 vcc, v198, v166
	v_subrev_u32_e32 v198, 47, v32
	s_nop 0
	v_cndmask_b32_e32 v137, v208, v137, vcc
	v_cmp_le_i32_e32 vcc, v198, v166
	v_add_u32_e32 v198, -15, v32
	s_nop 0
	v_cndmask_b32_e32 v122, v208, v122, vcc
	v_cmp_le_i32_e32 vcc, v198, v166
	v_subrev_u32_e32 v198, 46, v32
	s_nop 0
	v_cndmask_b32_e32 v138, v208, v138, vcc
	v_cmp_le_i32_e32 vcc, v198, v166
	v_add_u32_e32 v198, -14, v32
	s_nop 0
	v_cndmask_b32_e32 v123, v208, v123, vcc
	v_cmp_le_i32_e32 vcc, v198, v166
	v_subrev_u32_e32 v198, 45, v32
	s_nop 0
	v_cndmask_b32_e32 v139, v208, v139, vcc
	v_cmp_le_i32_e32 vcc, v198, v166
	v_add_u32_e32 v198, -13, v32
	s_nop 0
	v_cndmask_b32_e32 v124, v208, v124, vcc
	v_cmp_le_i32_e32 vcc, v198, v166
	v_subrev_u32_e32 v198, 44, v32
	s_nop 0
	v_cndmask_b32_e32 v140, v208, v140, vcc
	v_cmp_le_i32_e32 vcc, v198, v166
	v_add_u32_e32 v198, -12, v32
	s_nop 0
	v_cndmask_b32_e32 v125, v208, v125, vcc
	v_cmp_le_i32_e32 vcc, v198, v166
	v_subrev_u32_e32 v198, 39, v32
	s_nop 0
	v_cndmask_b32_e32 v141, v208, v141, vcc
	v_cmp_le_i32_e32 vcc, v198, v166
	v_add_u32_e32 v198, -7, v32
	s_nop 0
	v_cndmask_b32_e32 v126, v208, v126, vcc
	v_cmp_le_i32_e32 vcc, v198, v166
	v_subrev_u32_e32 v198, 38, v32
	s_nop 0
	v_cndmask_b32_e32 v142, v208, v142, vcc
	v_cmp_le_i32_e32 vcc, v198, v166
	v_add_u32_e32 v198, -6, v32
	s_nop 0
	v_cndmask_b32_e32 v127, v208, v127, vcc
	v_cmp_le_i32_e32 vcc, v198, v166
	v_subrev_u32_e32 v198, 37, v32
	s_nop 0
	v_cndmask_b32_e32 v143, v208, v143, vcc
	v_cmp_le_i32_e32 vcc, v198, v166
	v_add_u32_e32 v198, -5, v32
	s_nop 0
	v_cndmask_b32_e32 v128, v208, v128, vcc
	v_cmp_le_i32_e32 vcc, v198, v166
	v_subrev_u32_e32 v198, 36, v32
	v_add_u32_e32 v32, -4, v32
	v_cndmask_b32_e32 v144, v208, v144, vcc
	v_cmp_le_i32_e32 vcc, v198, v166
	s_nop 1
	v_cndmask_b32_e32 v129, v208, v129, vcc
	v_cmp_le_i32_e32 vcc, v32, v166
	s_nop 1
	v_cndmask_b32_e32 v145, v208, v145, vcc

.LBB0_637:
	s_mulk_i32 s24, 0x5000
	v_add_u32_e32 v32, s24, v194
	ds_read_b64_tr_b16 v[214:215], v32 offset:18432
	ds_read_b64_tr_b16 v[216:217], v32 offset:20992
	ds_read_b64_tr_b16 v[218:219], v32 offset:18496
	ds_read_b64_tr_b16 v[220:221], v32 offset:21056
	ds_read_b64_tr_b16 v[222:223], v32 offset:18560
	ds_read_b64_tr_b16 v[224:225], v32 offset:21120
	ds_read_b64_tr_b16 v[226:227], v32 offset:18624
	ds_read_b64_tr_b16 v[228:229], v32 offset:21184
	ds_read_b64_tr_b16 v[230:231], v32 offset:23552
	ds_read_b64_tr_b16 v[232:233], v32 offset:26112
	v_exp_f32_e32 v114, v114
	v_exp_f32_e32 v115, v115
	v_exp_f32_e32 v116, v116
	v_exp_f32_e32 v117, v117
	v_exp_f32_e32 v118, v118
	v_cvt_pk_bf16_f32 v234, v114, v115
	v_exp_f32_e32 v119, v119
	v_cvt_pk_bf16_f32 v235, v116, v117
	v_exp_f32_e32 v120, v120
	v_exp_f32_e32 v121, v121
	v_cvt_pk_bf16_f32 v236, v118, v119
	s_nop 0
	v_cvt_pk_bf16_f32 v237, v120, v121
	s_nop 1
	s_waitcnt lgkmcnt(8)
	v_mfma_f32_32x32x16_bf16 v[82:97], v[234:237], v[214:217], v[82:97]
	ds_read_b64_tr_b16 v[214:215], v32 offset:23616
	ds_read_b64_tr_b16 v[216:217], v32 offset:26176
	v_exp_f32_e32 v122, v122
	v_exp_f32_e32 v123, v123
	v_exp_f32_e32 v124, v124
	s_waitcnt lgkmcnt(8)
	v_mfma_f32_32x32x16_bf16 v[66:81], v[234:237], v[218:221], v[66:81]
	ds_read_b64_tr_b16 v[218:219], v32 offset:23680
	ds_read_b64_tr_b16 v[220:221], v32 offset:26240
	v_exp_f32_e32 v125, v125
	v_exp_f32_e32 v126, v126
	v_exp_f32_e32 v127, v127
	v_cvt_pk_bf16_f32 v238, v122, v123
	v_add_f32_e32 v252, v114, v115
	s_waitcnt lgkmcnt(8)
	v_mfma_f32_32x32x16_bf16 v[50:65], v[234:237], v[222:225], v[50:65]
	ds_read_b64_tr_b16 v[222:223], v32 offset:23744
	ds_read_b64_tr_b16 v[224:225], v32 offset:26304
	v_exp_f32_e32 v128, v128
	v_exp_f32_e32 v129, v129
	v_cvt_pk_bf16_f32 v239, v124, v125
	v_add_f32_e32 v253, v116, v117
	s_waitcnt lgkmcnt(8)
	v_mfma_f32_32x32x16_bf16 v[34:49], v[234:237], v[226:229], v[34:49]
	ds_read_b64_tr_b16 v[226:227], v32 offset:28672
	ds_read_b64_tr_b16 v[228:229], v32 offset:31232
	v_cvt_pk_bf16_f32 v240, v126, v127
	v_cvt_pk_bf16_f32 v241, v128, v129
	v_add_f32_e32 v254, v118, v119
	v_add_f32_e32 v213, v120, v121
	s_waitcnt lgkmcnt(8)
	v_mfma_f32_32x32x16_bf16 v[82:97], v[238:241], v[230:233], v[82:97]
	ds_read_b64_tr_b16 v[230:231], v32 offset:28736
	ds_read_b64_tr_b16 v[232:233], v32 offset:31296
	v_exp_f32_e32 v130, v130
	v_exp_f32_e32 v131, v131
	v_exp_f32_e32 v132, v132
	v_add_f32_e32 v252, v252, v122
	s_waitcnt lgkmcnt(8)
	v_mfma_f32_32x32x16_bf16 v[66:81], v[238:241], v[214:217], v[66:81]
	ds_read_b64_tr_b16 v[214:215], v32 offset:28800
	ds_read_b64_tr_b16 v[216:217], v32 offset:31360
	v_exp_f32_e32 v133, v133
	v_exp_f32_e32 v134, v134
	v_exp_f32_e32 v135, v135
	v_cvt_pk_bf16_f32 v244, v130, v131
	v_add_f32_e32 v253, v253, v123
	s_waitcnt lgkmcnt(8)
	v_mfma_f32_32x32x16_bf16 v[50:65], v[238:241], v[218:221], v[50:65]
	ds_read_b64_tr_b16 v[218:219], v32 offset:28864
	ds_read_b64_tr_b16 v[220:221], v32 offset:31424
	v_exp_f32_e32 v136, v136
	v_exp_f32_e32 v137, v137
	v_cvt_pk_bf16_f32 v245, v132, v133
	v_add_f32_e32 v254, v254, v124
	v_add_f32_e32 v213, v213, v125
	s_waitcnt lgkmcnt(8)
	v_mfma_f32_32x32x16_bf16 v[34:49], v[238:241], v[222:225], v[34:49]
	ds_read_b64_tr_b16 v[222:223], v32 offset:33792
	ds_read_b64_tr_b16 v[224:225], v32 offset:36352
	v_cvt_pk_bf16_f32 v246, v134, v135
	v_add_f32_e32 v252, v252, v126
	v_cvt_pk_bf16_f32 v247, v136, v137
	v_add_f32_e32 v253, v253, v127
	v_add_f32_e32 v254, v254, v128
	v_add_f32_e32 v213, v213, v129
	s_waitcnt lgkmcnt(8)
	v_mfma_f32_32x32x16_bf16 v[82:97], v[244:247], v[226:229], v[82:97]
	ds_read_b64_tr_b16 v[226:227], v32 offset:33856
	ds_read_b64_tr_b16 v[228:229], v32 offset:36416
	v_exp_f32_e32 v138, v138
	v_exp_f32_e32 v139, v139
	v_exp_f32_e32 v140, v140
	v_add_f32_e32 v252, v252, v130
	s_waitcnt lgkmcnt(8)
	v_mfma_f32_32x32x16_bf16 v[66:81], v[244:247], v[230:233], v[66:81]
	ds_read_b64_tr_b16 v[230:231], v32 offset:33920
	ds_read_b64_tr_b16 v[232:233], v32 offset:36480
	v_exp_f32_e32 v141, v141
	v_exp_f32_e32 v142, v142
	v_exp_f32_e32 v143, v143
	v_cvt_pk_bf16_f32 v248, v138, v139
	v_add_f32_e32 v253, v253, v131
	s_waitcnt lgkmcnt(8)
	v_mfma_f32_32x32x16_bf16 v[50:65], v[244:247], v[214:217], v[50:65]
	ds_read_b64_tr_b16 v[214:215], v32 offset:33984
	ds_read_b64_tr_b16 v[216:217], v32 offset:36544
	v_exp_f32_e32 v144, v144
	v_exp_f32_e32 v145, v145
	v_cvt_pk_bf16_f32 v249, v140, v141
	v_add_f32_e32 v254, v254, v132
	v_add_f32_e32 v213, v213, v133
	s_waitcnt lgkmcnt(8)
	v_mfma_f32_32x32x16_bf16 v[34:49], v[244:247], v[218:221], v[34:49]
	v_cvt_pk_bf16_f32 v250, v142, v143
	v_add_f32_e32 v252, v252, v134
	v_cvt_pk_bf16_f32 v251, v144, v145
	v_add_f32_e32 v253, v253, v135
	v_add_f32_e32 v254, v254, v136
	v_add_f32_e32 v213, v213, v137
	s_waitcnt lgkmcnt(6)
	v_mfma_f32_32x32x16_bf16 v[82:97], v[248:251], v[222:225], v[82:97]
	v_add_f32_e32 v252, v252, v138
	v_add_f32_e32 v253, v253, v139
	v_add_f32_e32 v254, v254, v140
	s_waitcnt lgkmcnt(4)
	v_mfma_f32_32x32x16_bf16 v[66:81], v[248:251], v[226:229], v[66:81]
	v_add_f32_e32 v213, v213, v141
	v_add_f32_e32 v252, v252, v142
	v_add_f32_e32 v253, v253, v143
	s_waitcnt lgkmcnt(2)
	v_mfma_f32_32x32x16_bf16 v[50:65], v[248:251], v[230:233], v[50:65]
	v_add_f32_e32 v254, v254, v144
	v_add_f32_e32 v213, v213, v145
	v_add_f32_e32 v252, v252, v253
	v_add_f32_e32 v254, v254, v213
	s_waitcnt lgkmcnt(0)
	v_mfma_f32_32x32x16_bf16 v[34:49], v[248:251], v[214:217], v[34:49]
	v_add_f32_e32 v252, v252, v254
	v_add_f32_e32 v182, v182, v252

.Lskip_v2_1:
.LBB0_825:
	s_sub_i32 s73, s18, 63
	s_cmp_gt_i32 s73, s26
	s_cbranch_scc1 .LBB0_838
	s_bitcmp1_b32 s72, 0
	s_cselect_b32 s72, 0x2400, 0
	v_add_u32_e32 v32, s72, v188
	ds_read_b128 v[214:217], v32
	ds_read_b128 v[218:221], v32 offset:4608
	ds_read_b128 v[222:225], v32 offset:32
	ds_read_b128 v[226:229], v32 offset:4640
	ds_read_b128 v[230:233], v32 offset:64
	ds_read_b128 v[234:237], v32 offset:4672
	ds_read_b128 v[238:241], v32 offset:96
	ds_read_b128 v[244:247], v32 offset:4704
	s_waitcnt lgkmcnt(7)
	v_mfma_f32_32x32x16_bf16 v[114:129], v[214:217], v[146:149], v[98:113]
	s_waitcnt lgkmcnt(6)
	v_mfma_f32_32x32x16_bf16 v[130:145], v[218:221], v[146:149], v[98:113]
	s_waitcnt lgkmcnt(5)
	v_mfma_f32_32x32x16_bf16 v[114:129], v[222:225], v[150:153], v[114:129]
	s_waitcnt lgkmcnt(4)
	v_mfma_f32_32x32x16_bf16 v[130:145], v[226:229], v[150:153], v[130:145]
	s_waitcnt lgkmcnt(3)
	v_mfma_f32_32x32x16_bf16 v[114:129], v[230:233], v[154:157], v[114:129]
	s_waitcnt lgkmcnt(2)
	v_mfma_f32_32x32x16_bf16 v[130:145], v[234:237], v[154:157], v[130:145]
	s_waitcnt lgkmcnt(1)
	v_mfma_f32_32x32x16_bf16 v[114:129], v[238:241], v[158:161], v[114:129]
	s_waitcnt lgkmcnt(0)
	v_mfma_f32_32x32x16_bf16 v[130:145], v[244:247], v[158:161], v[130:145]
	s_cmp_le_i32 s18, s76
	s_cbranch_scc1 .LBB0_828
	v_add_u32_e32 v32, s18, v190
	v_subrev_u32_e32 v200, 31, v32
	v_subrev_u32_e32 v198, 63, v32
	v_cmp_le_i32_e32 vcc, v200, v166
	s_nop 4
	v_cndmask_b32_e32 v130, v208, v130, vcc
	v_cmp_lt_i32_e32 vcc, v198, v166
	s_nop 1
	v_cndmask_b32_e32 v115, v208, v115, vcc
	v_cmp_le_i32_e32 vcc, v198, v166
	v_subrev_u32_e32 v198, 30, v32
	s_nop 0
	v_cndmask_b32_e32 v114, v208, v114, vcc
	v_cmp_le_i32_e32 vcc, v198, v166
	v_subrev_u32_e32 v198, 61, v32
	s_nop 0
	v_cndmask_b32_e32 v131, v208, v131, vcc
	v_cmp_le_i32_e32 vcc, v198, v166
	v_subrev_u32_e32 v198, 29, v32
	s_nop 0
	v_cndmask_b32_e32 v116, v208, v116, vcc
	v_cmp_le_i32_e32 vcc, v198, v166
	v_subrev_u32_e32 v198, 60, v32
	s_nop 0
	v_cndmask_b32_e32 v132, v208, v132, vcc
	v_cmp_le_i32_e32 vcc, v198, v166
	v_subrev_u32_e32 v198, 28, v32
	s_nop 0
	v_cndmask_b32_e32 v117, v208, v117, vcc
	v_cmp_le_i32_e32 vcc, v198, v166
	v_subrev_u32_e32 v198, 55, v32
	s_nop 0
	v_cndmask_b32_e32 v133, v208, v133, vcc
	v_cmp_le_i32_e32 vcc, v198, v166
	v_subrev_u32_e32 v198, 23, v32
	s_nop 0
	v_cndmask_b32_e32 v118, v208, v118, vcc
	v_cmp_le_i32_e32 vcc, v198, v166
	v_subrev_u32_e32 v198, 54, v32
	s_nop 0
	v_cndmask_b32_e32 v134, v208, v134, vcc
	v_cmp_le_i32_e32 vcc, v198, v166
	v_subrev_u32_e32 v198, 22, v32
	s_nop 0
	v_cndmask_b32_e32 v119, v208, v119, vcc
	v_cmp_le_i32_e32 vcc, v198, v166
	v_subrev_u32_e32 v198, 53, v32
	s_nop 0
	v_cndmask_b32_e32 v135, v208, v135, vcc
	v_cmp_le_i32_e32 vcc, v198, v166
	v_subrev_u32_e32 v198, 21, v32
	s_nop 0
	v_cndmask_b32_e32 v120, v208, v120, vcc
	v_cmp_le_i32_e32 vcc, v198, v166
	v_subrev_u32_e32 v198, 52, v32
	s_nop 0
	v_cndmask_b32_e32 v136, v208, v136, vcc
	v_cmp_le_i32_e32 vcc, v198, v166
	v_subrev_u32_e32 v198, 20, v32
	s_nop 0
	v_cndmask_b32_e32 v121, v208, v121, vcc
	v_cmp_le_i32_e32 vcc, v198, v166
	v_subrev_u32_e32 v198, 47, v32
	s_nop 0
	v_cndmask_b32_e32 v137, v208, v137, vcc
	v_cmp_le_i32_e32 vcc, v198, v166
	v_add_u32_e32 v198, -15, v32
	s_nop 0
	v_cndmask_b32_e32 v122, v208, v122, vcc
	v_cmp_le_i32_e32 vcc, v198, v166
	v_subrev_u32_e32 v198, 46, v32
	s_nop 0
	v_cndmask_b32_e32 v138, v208, v138, vcc
	v_cmp_le_i32_e32 vcc, v198, v166
	v_add_u32_e32 v198, -14, v32
	s_nop 0
	v_cndmask_b32_e32 v123, v208, v123, vcc
	v_cmp_le_i32_e32 vcc, v198, v166
	v_subrev_u32_e32 v198, 45, v32
	s_nop 0
	v_cndmask_b32_e32 v139, v208, v139, vcc
	v_cmp_le_i32_e32 vcc, v198, v166
	v_add_u32_e32 v198, -13, v32
	s_nop 0
	v_cndmask_b32_e32 v124, v208, v124, vcc
	v_cmp_le_i32_e32 vcc, v198, v166
	v_subrev_u32_e32 v198, 44, v32
	s_nop 0
	v_cndmask_b32_e32 v140, v208, v140, vcc
	v_cmp_le_i32_e32 vcc, v198, v166
	v_add_u32_e32 v198, -12, v32
	s_nop 0
	v_cndmask_b32_e32 v125, v208, v125, vcc
	v_cmp_le_i32_e32 vcc, v198, v166
	v_subrev_u32_e32 v198, 39, v32
	s_nop 0
	v_cndmask_b32_e32 v141, v208, v141, vcc
	v_cmp_le_i32_e32 vcc, v198, v166
	v_add_u32_e32 v198, -7, v32
	s_nop 0
	v_cndmask_b32_e32 v126, v208, v126, vcc
	v_cmp_le_i32_e32 vcc, v198, v166
	v_subrev_u32_e32 v198, 38, v32
	s_nop 0
	v_cndmask_b32_e32 v142, v208, v142, vcc
	v_cmp_le_i32_e32 vcc, v198, v166
	v_add_u32_e32 v198, -6, v32
	s_nop 0
	v_cndmask_b32_e32 v127, v208, v127, vcc
	v_cmp_le_i32_e32 vcc, v198, v166
	v_subrev_u32_e32 v198, 37, v32
	s_nop 0
	v_cndmask_b32_e32 v143, v208, v143, vcc
	v_cmp_le_i32_e32 vcc, v198, v166
	v_add_u32_e32 v198, -5, v32
	s_nop 0
	v_cndmask_b32_e32 v128, v208, v128, vcc
	v_cmp_le_i32_e32 vcc, v198, v166
	v_subrev_u32_e32 v198, 36, v32
	v_add_u32_e32 v32, -4, v32
	v_cndmask_b32_e32 v144, v208, v144, vcc
	v_cmp_le_i32_e32 vcc, v198, v166
	s_nop 1
	v_cndmask_b32_e32 v129, v208, v129, vcc
	v_cmp_le_i32_e32 vcc, v32, v166
	s_nop 1
	v_cndmask_b32_e32 v145, v208, v145, vcc

.LBB0_837:
	s_mulk_i32 s35, 0x5000
	v_add_u32_e32 v32, s35, v194
	ds_read_b64_tr_b16 v[214:215], v32 offset:18432
	ds_read_b64_tr_b16 v[216:217], v32 offset:20992
	ds_read_b64_tr_b16 v[218:219], v32 offset:18496
	ds_read_b64_tr_b16 v[220:221], v32 offset:21056
	ds_read_b64_tr_b16 v[222:223], v32 offset:18560
	ds_read_b64_tr_b16 v[224:225], v32 offset:21120
	ds_read_b64_tr_b16 v[226:227], v32 offset:18624
	ds_read_b64_tr_b16 v[228:229], v32 offset:21184
	ds_read_b64_tr_b16 v[230:231], v32 offset:23552
	ds_read_b64_tr_b16 v[232:233], v32 offset:26112
	v_exp_f32_e32 v114, v114
	v_exp_f32_e32 v115, v115
	v_exp_f32_e32 v116, v116
	v_exp_f32_e32 v117, v117
	v_exp_f32_e32 v118, v118
	v_cvt_pk_bf16_f32 v234, v114, v115
	v_exp_f32_e32 v119, v119
	v_cvt_pk_bf16_f32 v235, v116, v117
	v_exp_f32_e32 v120, v120
	v_exp_f32_e32 v121, v121
	v_cvt_pk_bf16_f32 v236, v118, v119
	s_nop 0
	v_cvt_pk_bf16_f32 v237, v120, v121
	s_nop 1
	s_waitcnt lgkmcnt(8)
	v_mfma_f32_32x32x16_bf16 v[82:97], v[234:237], v[214:217], v[82:97]
	ds_read_b64_tr_b16 v[214:215], v32 offset:23616
	ds_read_b64_tr_b16 v[216:217], v32 offset:26176
	v_exp_f32_e32 v122, v122
	v_exp_f32_e32 v123, v123
	v_exp_f32_e32 v124, v124
	s_waitcnt lgkmcnt(8)
	v_mfma_f32_32x32x16_bf16 v[66:81], v[234:237], v[218:221], v[66:81]
	ds_read_b64_tr_b16 v[218:219], v32 offset:23680
	ds_read_b64_tr_b16 v[220:221], v32 offset:26240
	v_exp_f32_e32 v125, v125
	v_exp_f32_e32 v126, v126
	v_exp_f32_e32 v127, v127
	v_cvt_pk_bf16_f32 v238, v122, v123
	v_add_f32_e32 v252, v114, v115
	s_waitcnt lgkmcnt(8)
	v_mfma_f32_32x32x16_bf16 v[50:65], v[234:237], v[222:225], v[50:65]
	ds_read_b64_tr_b16 v[222:223], v32 offset:23744
	ds_read_b64_tr_b16 v[224:225], v32 offset:26304
	v_exp_f32_e32 v128, v128
	v_exp_f32_e32 v129, v129
	v_cvt_pk_bf16_f32 v239, v124, v125
	v_add_f32_e32 v253, v116, v117
	s_waitcnt lgkmcnt(8)
	v_mfma_f32_32x32x16_bf16 v[34:49], v[234:237], v[226:229], v[34:49]
	ds_read_b64_tr_b16 v[226:227], v32 offset:28672
	ds_read_b64_tr_b16 v[228:229], v32 offset:31232
	v_cvt_pk_bf16_f32 v240, v126, v127
	v_cvt_pk_bf16_f32 v241, v128, v129
	v_add_f32_e32 v254, v118, v119
	v_add_f32_e32 v213, v120, v121
	s_waitcnt lgkmcnt(8)
	v_mfma_f32_32x32x16_bf16 v[82:97], v[238:241], v[230:233], v[82:97]
	ds_read_b64_tr_b16 v[230:231], v32 offset:28736
	ds_read_b64_tr_b16 v[232:233], v32 offset:31296
	v_exp_f32_e32 v130, v130
	v_exp_f32_e32 v131, v131
	v_exp_f32_e32 v132, v132
	v_add_f32_e32 v252, v252, v122
	s_waitcnt lgkmcnt(8)
	v_mfma_f32_32x32x16_bf16 v[66:81], v[238:241], v[214:217], v[66:81]
	ds_read_b64_tr_b16 v[214:215], v32 offset:28800
	ds_read_b64_tr_b16 v[216:217], v32 offset:31360
	v_exp_f32_e32 v133, v133
	v_exp_f32_e32 v134, v134
	v_exp_f32_e32 v135, v135
	v_cvt_pk_bf16_f32 v244, v130, v131
	v_add_f32_e32 v253, v253, v123
	s_waitcnt lgkmcnt(8)
	v_mfma_f32_32x32x16_bf16 v[50:65], v[238:241], v[218:221], v[50:65]
	ds_read_b64_tr_b16 v[218:219], v32 offset:28864
	ds_read_b64_tr_b16 v[220:221], v32 offset:31424
	v_exp_f32_e32 v136, v136
	v_exp_f32_e32 v137, v137
	v_cvt_pk_bf16_f32 v245, v132, v133
	v_add_f32_e32 v254, v254, v124
	v_add_f32_e32 v213, v213, v125
	s_waitcnt lgkmcnt(8)
	v_mfma_f32_32x32x16_bf16 v[34:49], v[238:241], v[222:225], v[34:49]
	ds_read_b64_tr_b16 v[222:223], v32 offset:33792
	ds_read_b64_tr_b16 v[224:225], v32 offset:36352
	v_cvt_pk_bf16_f32 v246, v134, v135
	v_add_f32_e32 v252, v252, v126
	v_cvt_pk_bf16_f32 v247, v136, v137
	v_add_f32_e32 v253, v253, v127
	v_add_f32_e32 v254, v254, v128
	v_add_f32_e32 v213, v213, v129
	s_waitcnt lgkmcnt(8)
	v_mfma_f32_32x32x16_bf16 v[82:97], v[244:247], v[226:229], v[82:97]
	ds_read_b64_tr_b16 v[226:227], v32 offset:33856
	ds_read_b64_tr_b16 v[228:229], v32 offset:36416
	v_exp_f32_e32 v138, v138
	v_exp_f32_e32 v139, v139
	v_exp_f32_e32 v140, v140
	v_add_f32_e32 v252, v252, v130
	s_waitcnt lgkmcnt(8)
	v_mfma_f32_32x32x16_bf16 v[66:81], v[244:247], v[230:233], v[66:81]
	ds_read_b64_tr_b16 v[230:231], v32 offset:33920
	ds_read_b64_tr_b16 v[232:233], v32 offset:36480
	v_exp_f32_e32 v141, v141
	v_exp_f32_e32 v142, v142
	v_exp_f32_e32 v143, v143
	v_cvt_pk_bf16_f32 v248, v138, v139
	v_add_f32_e32 v253, v253, v131
	s_waitcnt lgkmcnt(8)
	v_mfma_f32_32x32x16_bf16 v[50:65], v[244:247], v[214:217], v[50:65]
	ds_read_b64_tr_b16 v[214:215], v32 offset:33984
	ds_read_b64_tr_b16 v[216:217], v32 offset:36544
	v_exp_f32_e32 v144, v144
	v_exp_f32_e32 v145, v145
	v_cvt_pk_bf16_f32 v249, v140, v141
	v_add_f32_e32 v254, v254, v132
	v_add_f32_e32 v213, v213, v133
	s_waitcnt lgkmcnt(8)
	v_mfma_f32_32x32x16_bf16 v[34:49], v[244:247], v[218:221], v[34:49]
	v_cvt_pk_bf16_f32 v250, v142, v143
	v_add_f32_e32 v252, v252, v134
	v_cvt_pk_bf16_f32 v251, v144, v145
	v_add_f32_e32 v253, v253, v135
	v_add_f32_e32 v254, v254, v136
	v_add_f32_e32 v213, v213, v137
	s_waitcnt lgkmcnt(6)
	v_mfma_f32_32x32x16_bf16 v[82:97], v[248:251], v[222:225], v[82:97]
	v_add_f32_e32 v252, v252, v138
	v_add_f32_e32 v253, v253, v139
	v_add_f32_e32 v254, v254, v140
	s_waitcnt lgkmcnt(4)
	v_mfma_f32_32x32x16_bf16 v[66:81], v[248:251], v[226:229], v[66:81]
	v_add_f32_e32 v213, v213, v141
	v_add_f32_e32 v252, v252, v142
	v_add_f32_e32 v253, v253, v143
	s_waitcnt lgkmcnt(2)
	v_mfma_f32_32x32x16_bf16 v[50:65], v[248:251], v[230:233], v[50:65]
	v_add_f32_e32 v254, v254, v144
	v_add_f32_e32 v213, v213, v145
	v_add_f32_e32 v252, v252, v253
	v_add_f32_e32 v254, v254, v213
	s_waitcnt lgkmcnt(0)
	v_mfma_f32_32x32x16_bf16 v[34:49], v[248:251], v[214:217], v[34:49]
	v_add_f32_e32 v252, v252, v254
	v_add_f32_e32 v182, v182, v252

.Lskip_v2_2_p0:
.LBB0_2155_p0:
	s_sub_i32 s61, s75, 63
	s_cmp_gt_i32 s61, s25
	s_cbranch_scc1 .Lnovis_p0
	s_bitcmp1_b32 s60, 0
	s_cselect_b32 s60, 0x6400, 0
	v_add_u32_e32 v0, s60, v200
	ds_read_b128 v[238:241], v0
	ds_read_b128 v[244:247], v0 offset:32
	ds_read_b128 v[248:251], v0 offset:12800
	ds_read_b128 v[8:11], v0 offset:12832
	ds_read_b128 v[12:15], v0 offset:64
	s_waitcnt lgkmcnt(4)
	v_mfma_f32_32x32x16_bf16 v[96:111], v[238:241], v[128:131], v[80:95]
	ds_read_b128 v[238:241], v0 offset:12864
	s_waitcnt lgkmcnt(4)
	v_mfma_f32_32x32x16_bf16 v[96:111], v[244:247], v[132:135], v[96:111]
	ds_read_b128 v[244:247], v0 offset:96
	s_waitcnt lgkmcnt(4)
	v_mfma_f32_32x32x16_bf16 v[112:127], v[248:251], v[128:131], v[80:95]
	ds_read_b128 v[248:251], v0 offset:12896
	s_waitcnt lgkmcnt(4)
	v_mfma_f32_32x32x16_bf16 v[112:127], v[8:11], v[132:135], v[112:127]
	ds_read_b128 v[8:11], v0 offset:128
	s_waitcnt lgkmcnt(4)
	v_mfma_f32_32x32x16_bf16 v[96:111], v[12:15], v[136:139], v[96:111]
	ds_read_b128 v[12:15], v0 offset:12928
	s_waitcnt lgkmcnt(4)
	v_mfma_f32_32x32x16_bf16 v[112:127], v[238:241], v[136:139], v[112:127]
	ds_read_b128 v[238:241], v0 offset:160
	s_waitcnt lgkmcnt(4)
	v_mfma_f32_32x32x16_bf16 v[96:111], v[244:247], v[140:143], v[96:111]
	ds_read_b128 v[244:247], v0 offset:12960
	s_waitcnt lgkmcnt(4)
	v_mfma_f32_32x32x16_bf16 v[112:127], v[248:251], v[140:143], v[112:127]
	ds_read_b128 v[248:251], v0 offset:192
	s_waitcnt lgkmcnt(4)
	v_mfma_f32_32x32x16_bf16 v[96:111], v[8:11], v[144:147], v[96:111]
	ds_read_b128 v[8:11], v0 offset:12992
	s_waitcnt lgkmcnt(4)
	v_mfma_f32_32x32x16_bf16 v[112:127], v[12:15], v[144:147], v[112:127]
	ds_read_b128 v[12:15], v0 offset:224
	s_waitcnt lgkmcnt(4)
	v_mfma_f32_32x32x16_bf16 v[96:111], v[238:241], v[148:151], v[96:111]
	ds_read_b128 v[238:241], v0 offset:13024
	s_waitcnt lgkmcnt(4)
	v_mfma_f32_32x32x16_bf16 v[112:127], v[244:247], v[148:151], v[112:127]
	ds_read_b128 v[244:247], v0 offset:256
	s_waitcnt lgkmcnt(4)
	v_mfma_f32_32x32x16_bf16 v[96:111], v[248:251], v[152:155], v[96:111]
	ds_read_b128 v[248:251], v0 offset:13056
	s_waitcnt lgkmcnt(4)
	v_mfma_f32_32x32x16_bf16 v[112:127], v[8:11], v[152:155], v[112:127]
	ds_read_b128 v[8:11], v0 offset:288
	s_waitcnt lgkmcnt(4)
	v_mfma_f32_32x32x16_bf16 v[96:111], v[12:15], v[156:159], v[96:111]
	ds_read_b128 v[12:15], v0 offset:13088
	s_waitcnt lgkmcnt(4)
	v_mfma_f32_32x32x16_bf16 v[112:127], v[238:241], v[156:159], v[112:127]
	ds_read_b128 v[238:241], v0 offset:320
	s_waitcnt lgkmcnt(4)
	v_mfma_f32_32x32x16_bf16 v[96:111], v[244:247], v[160:163], v[96:111]
	ds_read_b128 v[244:247], v0 offset:13120
	s_waitcnt lgkmcnt(4)
	v_mfma_f32_32x32x16_bf16 v[112:127], v[248:251], v[160:163], v[112:127]
	ds_read_b128 v[248:251], v0 offset:352
	s_waitcnt lgkmcnt(4)
	v_mfma_f32_32x32x16_bf16 v[96:111], v[8:11], v[164:167], v[96:111]
	ds_read_b128 v[8:11], v0 offset:13152
	s_waitcnt lgkmcnt(4)
	v_mfma_f32_32x32x16_bf16 v[112:127], v[12:15], v[164:167], v[112:127]
	s_waitcnt lgkmcnt(3)
	v_mfma_f32_32x32x16_bf16 v[96:111], v[238:241], v[168:171], v[96:111]
	s_waitcnt lgkmcnt(2)
	v_mfma_f32_32x32x16_bf16 v[112:127], v[244:247], v[168:171], v[112:127]
	s_waitcnt lgkmcnt(1)
	v_mfma_f32_32x32x16_bf16 v[96:111], v[248:251], v[172:175], v[96:111]
	s_waitcnt lgkmcnt(0)
	v_mfma_f32_32x32x16_bf16 v[112:127], v[8:11], v[172:175], v[112:127]
	s_cmp_le_i32 s75, s68
	s_cbranch_scc1 .Lmaskdone_p0
	v_add_u32_e32 v0, s75, v201
	v_subrev_u32_e32 v4, 31, v0
	v_subrev_u32_e32 v3, 63, v0
	v_cmp_le_i32_e32 vcc, v4, v197
	s_nop 4
	v_cndmask_b32_e32 v112, v194, v112, vcc
	v_cmp_lt_i32_e32 vcc, v3, v197
	s_nop 1
	v_cndmask_b32_e32 v97, v194, v97, vcc
	v_cmp_le_i32_e32 vcc, v3, v197
	v_subrev_u32_e32 v3, 30, v0
	s_nop 0
	v_cndmask_b32_e32 v96, v194, v96, vcc
	v_cmp_le_i32_e32 vcc, v3, v197
	v_subrev_u32_e32 v3, 61, v0
	s_nop 0
	v_cndmask_b32_e32 v113, v194, v113, vcc
	v_cmp_le_i32_e32 vcc, v3, v197
	v_subrev_u32_e32 v3, 29, v0
	s_nop 0
	v_cndmask_b32_e32 v98, v194, v98, vcc
	v_cmp_le_i32_e32 vcc, v3, v197
	v_subrev_u32_e32 v3, 60, v0
	s_nop 0
	v_cndmask_b32_e32 v114, v194, v114, vcc
	v_cmp_le_i32_e32 vcc, v3, v197
	v_subrev_u32_e32 v3, 28, v0
	s_nop 0
	v_cndmask_b32_e32 v99, v194, v99, vcc
	v_cmp_le_i32_e32 vcc, v3, v197
	v_subrev_u32_e32 v3, 55, v0
	s_nop 0
	v_cndmask_b32_e32 v115, v194, v115, vcc
	v_cmp_le_i32_e32 vcc, v3, v197
	v_subrev_u32_e32 v3, 23, v0
	s_nop 0
	v_cndmask_b32_e32 v100, v194, v100, vcc
	v_cmp_le_i32_e32 vcc, v3, v197
	v_subrev_u32_e32 v3, 54, v0
	s_nop 0
	v_cndmask_b32_e32 v116, v194, v116, vcc
	v_cmp_le_i32_e32 vcc, v3, v197
	v_subrev_u32_e32 v3, 22, v0
	s_nop 0
	v_cndmask_b32_e32 v101, v194, v101, vcc
	v_cmp_le_i32_e32 vcc, v3, v197
	v_subrev_u32_e32 v3, 53, v0
	s_nop 0
	v_cndmask_b32_e32 v117, v194, v117, vcc
	v_cmp_le_i32_e32 vcc, v3, v197
	v_subrev_u32_e32 v3, 21, v0
	s_nop 0
	v_cndmask_b32_e32 v102, v194, v102, vcc
	v_cmp_le_i32_e32 vcc, v3, v197
	v_subrev_u32_e32 v3, 52, v0
	s_nop 0
	v_cndmask_b32_e32 v118, v194, v118, vcc
	v_cmp_le_i32_e32 vcc, v3, v197
	v_subrev_u32_e32 v3, 20, v0
	s_nop 0
	v_cndmask_b32_e32 v103, v194, v103, vcc
	v_cmp_le_i32_e32 vcc, v3, v197
	v_subrev_u32_e32 v3, 47, v0
	s_nop 0
	v_cndmask_b32_e32 v119, v194, v119, vcc
	v_cmp_le_i32_e32 vcc, v3, v197
	v_add_u32_e32 v3, -15, v0
	s_nop 0
	v_cndmask_b32_e32 v104, v194, v104, vcc
	v_cmp_le_i32_e32 vcc, v3, v197
	v_subrev_u32_e32 v3, 46, v0
	s_nop 0
	v_cndmask_b32_e32 v120, v194, v120, vcc
	v_cmp_le_i32_e32 vcc, v3, v197
	v_add_u32_e32 v3, -14, v0
	s_nop 0
	v_cndmask_b32_e32 v105, v194, v105, vcc
	v_cmp_le_i32_e32 vcc, v3, v197
	v_subrev_u32_e32 v3, 45, v0
	s_nop 0
	v_cndmask_b32_e32 v121, v194, v121, vcc
	v_cmp_le_i32_e32 vcc, v3, v197
	v_add_u32_e32 v3, -13, v0
	s_nop 0
	v_cndmask_b32_e32 v106, v194, v106, vcc
	v_cmp_le_i32_e32 vcc, v3, v197
	v_subrev_u32_e32 v3, 44, v0
	s_nop 0
	v_cndmask_b32_e32 v122, v194, v122, vcc
	v_cmp_le_i32_e32 vcc, v3, v197
	v_add_u32_e32 v3, -12, v0
	s_nop 0
	v_cndmask_b32_e32 v107, v194, v107, vcc
	v_cmp_le_i32_e32 vcc, v3, v197
	v_subrev_u32_e32 v3, 39, v0
	s_nop 0
	v_cndmask_b32_e32 v123, v194, v123, vcc
	v_cmp_le_i32_e32 vcc, v3, v197
	v_add_u32_e32 v3, -7, v0
	s_nop 0
	v_cndmask_b32_e32 v108, v194, v108, vcc
	v_cmp_le_i32_e32 vcc, v3, v197
	v_subrev_u32_e32 v3, 38, v0
	s_nop 0
	v_cndmask_b32_e32 v124, v194, v124, vcc
	v_cmp_le_i32_e32 vcc, v3, v197
	v_add_u32_e32 v3, -6, v0
	s_nop 0
	v_cndmask_b32_e32 v109, v194, v109, vcc
	v_cmp_le_i32_e32 vcc, v3, v197
	v_subrev_u32_e32 v3, 37, v0
	s_nop 0
	v_cndmask_b32_e32 v125, v194, v125, vcc
	v_cmp_le_i32_e32 vcc, v3, v197
	v_add_u32_e32 v3, -5, v0
	s_nop 0
	v_cndmask_b32_e32 v110, v194, v110, vcc
	v_cmp_le_i32_e32 vcc, v3, v197
	v_subrev_u32_e32 v3, 36, v0
	v_add_u32_e32 v0, -4, v0
	v_cndmask_b32_e32 v126, v194, v126, vcc
	v_cmp_le_i32_e32 vcc, v3, v197
	s_nop 1
	v_cndmask_b32_e32 v111, v194, v111, vcc
	v_cmp_le_i32_e32 vcc, v0, v197
	s_nop 1
	v_cndmask_b32_e32 v127, v194, v127, vcc

.Lskip_v2_2_ba:
.LBB0_2155_ba:
	s_sub_i32 s61, s75, 63
	s_cmp_gt_i32 s61, s25
	s_cbranch_scc1 .Lnovis_ba
	s_bitcmp1_b32 s60, 0
	s_cselect_b32 s60, 0x6400, 0
	v_add_u32_e32 v0, s60, v200
	ds_read_b128 v[238:241], v0
	ds_read_b128 v[244:247], v0 offset:32
	ds_read_b128 v[248:251], v0 offset:12800
	ds_read_b128 v[8:11], v0 offset:12832
	ds_read_b128 v[12:15], v0 offset:64
	s_waitcnt lgkmcnt(4)
	v_mfma_f32_32x32x16_bf16 v[206:221], v[238:241], v[128:131], v[80:95]
	ds_read_b128 v[238:241], v0 offset:12864
	v_exp_f32_e32 v96, v96
	v_exp_f32_e32 v97, v97
	v_exp_f32_e32 v98, v98
	v_exp_f32_e32 v99, v99
	s_waitcnt lgkmcnt(4)
	v_mfma_f32_32x32x16_bf16 v[206:221], v[244:247], v[132:135], v[206:221]
	ds_read_b128 v[244:247], v0 offset:96
	v_exp_f32_e32 v100, v100
	v_exp_f32_e32 v101, v101
	v_exp_f32_e32 v102, v102
	s_waitcnt lgkmcnt(4)
	v_mfma_f32_32x32x16_bf16 v[222:237], v[248:251], v[128:131], v[80:95]
	ds_read_b128 v[248:251], v0 offset:12896
	v_exp_f32_e32 v103, v103
	v_exp_f32_e32 v104, v104
	v_exp_f32_e32 v105, v105
	s_waitcnt lgkmcnt(4)
	v_mfma_f32_32x32x16_bf16 v[222:237], v[8:11], v[132:135], v[222:237]
	ds_read_b128 v[8:11], v0 offset:128
	v_exp_f32_e32 v106, v106
	v_exp_f32_e32 v107, v107
	v_exp_f32_e32 v108, v108
	v_exp_f32_e32 v109, v109
	s_waitcnt lgkmcnt(4)
	v_mfma_f32_32x32x16_bf16 v[206:221], v[12:15], v[136:139], v[206:221]
	ds_read_b128 v[12:15], v0 offset:12928
	v_exp_f32_e32 v110, v110
	v_exp_f32_e32 v111, v111
	v_add_f32_e32 v252, v96, v97
	s_waitcnt lgkmcnt(4)
	v_mfma_f32_32x32x16_bf16 v[222:237], v[238:241], v[136:139], v[222:237]
	ds_read_b128 v[238:241], v0 offset:160
	v_add_f32_e32 v253, v98, v99
	v_add_f32_e32 v254, v100, v101
	v_add_f32_e32 v205, v102, v103
	s_waitcnt lgkmcnt(4)
	v_mfma_f32_32x32x16_bf16 v[206:221], v[244:247], v[140:143], v[206:221]
	ds_read_b128 v[244:247], v0 offset:12960
	v_cvt_pk_bf16_f32 v96, v96, v97
	v_cvt_pk_bf16_f32 v97, v98, v99
	v_cvt_pk_bf16_f32 v98, v100, v101
	v_cvt_pk_bf16_f32 v99, v102, v103
	s_waitcnt lgkmcnt(4)
	v_mfma_f32_32x32x16_bf16 v[222:237], v[248:251], v[140:143], v[222:237]
	ds_read_b128 v[248:251], v0 offset:192
	v_exp_f32_e32 v112, v112
	v_exp_f32_e32 v113, v113
	v_exp_f32_e32 v114, v114
	s_waitcnt lgkmcnt(4)
	v_mfma_f32_32x32x16_bf16 v[206:221], v[8:11], v[144:147], v[206:221]
	ds_read_b128 v[8:11], v0 offset:12992
	v_exp_f32_e32 v115, v115
	v_exp_f32_e32 v116, v116
	v_exp_f32_e32 v117, v117
	s_waitcnt lgkmcnt(4)
	v_mfma_f32_32x32x16_bf16 v[222:237], v[12:15], v[144:147], v[222:237]
	ds_read_b128 v[12:15], v0 offset:224
	v_exp_f32_e32 v118, v118
	v_exp_f32_e32 v119, v119
	v_add_f32_e32 v252, v252, v104
	v_add_f32_e32 v253, v253, v105
	s_waitcnt lgkmcnt(4)
	v_mfma_f32_32x32x16_bf16 v[206:221], v[238:241], v[148:151], v[206:221]
	ds_read_b128 v[238:241], v0 offset:13024
	v_add_f32_e32 v254, v254, v106
	v_add_f32_e32 v205, v205, v107
	v_add_f32_e32 v252, v252, v108
	s_waitcnt lgkmcnt(4)
	v_mfma_f32_32x32x16_bf16 v[222:237], v[244:247], v[148:151], v[222:237]
	ds_read_b128 v[244:247], v0 offset:256
	v_add_f32_e32 v253, v253, v109
	v_add_f32_e32 v254, v254, v110
	v_add_f32_e32 v205, v205, v111
	s_waitcnt lgkmcnt(4)
	v_mfma_f32_32x32x16_bf16 v[206:221], v[248:251], v[152:155], v[206:221]
	ds_read_b128 v[248:251], v0 offset:13056
	v_cvt_pk_bf16_f32 v104, v104, v105
	v_cvt_pk_bf16_f32 v105, v106, v107
	v_cvt_pk_bf16_f32 v106, v108, v109
	v_cvt_pk_bf16_f32 v107, v110, v111
	s_waitcnt lgkmcnt(4)
	v_mfma_f32_32x32x16_bf16 v[222:237], v[8:11], v[152:155], v[222:237]
	ds_read_b128 v[8:11], v0 offset:288
	v_exp_f32_e32 v120, v120
	v_exp_f32_e32 v121, v121
	v_exp_f32_e32 v122, v122
	s_waitcnt lgkmcnt(4)
	v_mfma_f32_32x32x16_bf16 v[206:221], v[12:15], v[156:159], v[206:221]
	ds_read_b128 v[12:15], v0 offset:13088
	v_exp_f32_e32 v123, v123
	v_exp_f32_e32 v124, v124
	v_exp_f32_e32 v125, v125
	s_waitcnt lgkmcnt(4)
	v_mfma_f32_32x32x16_bf16 v[222:237], v[238:241], v[156:159], v[222:237]
	ds_read_b128 v[238:241], v0 offset:320
	v_exp_f32_e32 v126, v126
	v_exp_f32_e32 v127, v127
	v_add_f32_e32 v252, v252, v112
	v_add_f32_e32 v253, v253, v113
	s_waitcnt lgkmcnt(4)
	v_mfma_f32_32x32x16_bf16 v[206:221], v[244:247], v[160:163], v[206:221]
	ds_read_b128 v[244:247], v0 offset:13120
	v_add_f32_e32 v254, v254, v114
	v_add_f32_e32 v205, v205, v115
	v_add_f32_e32 v252, v252, v116
	s_waitcnt lgkmcnt(4)
	v_mfma_f32_32x32x16_bf16 v[222:237], v[248:251], v[160:163], v[222:237]
	ds_read_b128 v[248:251], v0 offset:352
	v_add_f32_e32 v253, v253, v117
	v_add_f32_e32 v254, v254, v118
	v_add_f32_e32 v205, v205, v119
	s_waitcnt lgkmcnt(4)
	v_mfma_f32_32x32x16_bf16 v[206:221], v[8:11], v[164:167], v[206:221]
	ds_read_b128 v[8:11], v0 offset:13152
	v_cvt_pk_bf16_f32 v112, v112, v113
	v_cvt_pk_bf16_f32 v113, v114, v115
	v_cvt_pk_bf16_f32 v114, v116, v117
	v_cvt_pk_bf16_f32 v115, v118, v119
	s_waitcnt lgkmcnt(4)
	v_mfma_f32_32x32x16_bf16 v[222:237], v[12:15], v[164:167], v[222:237]
	v_add_f32_e32 v252, v252, v120
	v_add_f32_e32 v253, v253, v121
	v_add_f32_e32 v254, v254, v122
	s_waitcnt lgkmcnt(3)
	v_mfma_f32_32x32x16_bf16 v[206:221], v[238:241], v[168:171], v[206:221]
	v_add_f32_e32 v205, v205, v123
	v_add_f32_e32 v252, v252, v124
	v_add_f32_e32 v253, v253, v125
	s_waitcnt lgkmcnt(2)
	v_mfma_f32_32x32x16_bf16 v[222:237], v[244:247], v[168:171], v[222:237]
	v_add_f32_e32 v254, v254, v126
	v_add_f32_e32 v205, v205, v127
	v_cvt_pk_bf16_f32 v120, v120, v121
	v_cvt_pk_bf16_f32 v121, v122, v123
	s_waitcnt lgkmcnt(1)
	v_mfma_f32_32x32x16_bf16 v[206:221], v[248:251], v[172:175], v[206:221]
	v_cvt_pk_bf16_f32 v122, v124, v125
	v_cvt_pk_bf16_f32 v123, v126, v127
	v_add_f32_e32 v252, v252, v253
	s_waitcnt lgkmcnt(0)
	v_mfma_f32_32x32x16_bf16 v[222:237], v[8:11], v[172:175], v[222:237]
	v_add_f32_e32 v254, v254, v205
	v_add_f32_e32 v252, v252, v254
	v_add_f32_e32 v2, v2, v252
	s_cmp_le_i32 s75, s68
	s_cbranch_scc1 .Lmaskdone_ba
	v_add_u32_e32 v0, s75, v201
	v_subrev_u32_e32 v4, 31, v0
	v_subrev_u32_e32 v3, 63, v0
	v_cmp_le_i32_e32 vcc, v4, v197
	s_nop 4
	v_cndmask_b32_e32 v222, v194, v222, vcc
	v_cmp_lt_i32_e32 vcc, v3, v197
	s_nop 1
	v_cndmask_b32_e32 v207, v194, v207, vcc
	v_cmp_le_i32_e32 vcc, v3, v197
	v_subrev_u32_e32 v3, 30, v0
	s_nop 0
	v_cndmask_b32_e32 v206, v194, v206, vcc
	v_cmp_le_i32_e32 vcc, v3, v197
	v_subrev_u32_e32 v3, 61, v0
	s_nop 0
	v_cndmask_b32_e32 v223, v194, v223, vcc
	v_cmp_le_i32_e32 vcc, v3, v197
	v_subrev_u32_e32 v3, 29, v0
	s_nop 0
	v_cndmask_b32_e32 v208, v194, v208, vcc
	v_cmp_le_i32_e32 vcc, v3, v197
	v_subrev_u32_e32 v3, 60, v0
	s_nop 0
	v_cndmask_b32_e32 v224, v194, v224, vcc
	v_cmp_le_i32_e32 vcc, v3, v197
	v_subrev_u32_e32 v3, 28, v0
	s_nop 0
	v_cndmask_b32_e32 v209, v194, v209, vcc
	v_cmp_le_i32_e32 vcc, v3, v197
	v_subrev_u32_e32 v3, 55, v0
	s_nop 0
	v_cndmask_b32_e32 v225, v194, v225, vcc
	v_cmp_le_i32_e32 vcc, v3, v197
	v_subrev_u32_e32 v3, 23, v0
	s_nop 0
	v_cndmask_b32_e32 v210, v194, v210, vcc
	v_cmp_le_i32_e32 vcc, v3, v197
	v_subrev_u32_e32 v3, 54, v0
	s_nop 0
	v_cndmask_b32_e32 v226, v194, v226, vcc
	v_cmp_le_i32_e32 vcc, v3, v197
	v_subrev_u32_e32 v3, 22, v0
	s_nop 0
	v_cndmask_b32_e32 v211, v194, v211, vcc
	v_cmp_le_i32_e32 vcc, v3, v197
	v_subrev_u32_e32 v3, 53, v0
	s_nop 0
	v_cndmask_b32_e32 v227, v194, v227, vcc
	v_cmp_le_i32_e32 vcc, v3, v197
	v_subrev_u32_e32 v3, 21, v0
	s_nop 0
	v_cndmask_b32_e32 v212, v194, v212, vcc
	v_cmp_le_i32_e32 vcc, v3, v197
	v_subrev_u32_e32 v3, 52, v0
	s_nop 0
	v_cndmask_b32_e32 v228, v194, v228, vcc
	v_cmp_le_i32_e32 vcc, v3, v197
	v_subrev_u32_e32 v3, 20, v0
	s_nop 0
	v_cndmask_b32_e32 v213, v194, v213, vcc
	v_cmp_le_i32_e32 vcc, v3, v197
	v_subrev_u32_e32 v3, 47, v0
	s_nop 0
	v_cndmask_b32_e32 v229, v194, v229, vcc
	v_cmp_le_i32_e32 vcc, v3, v197
	v_add_u32_e32 v3, -15, v0
	s_nop 0
	v_cndmask_b32_e32 v214, v194, v214, vcc
	v_cmp_le_i32_e32 vcc, v3, v197
	v_subrev_u32_e32 v3, 46, v0
	s_nop 0
	v_cndmask_b32_e32 v230, v194, v230, vcc
	v_cmp_le_i32_e32 vcc, v3, v197
	v_add_u32_e32 v3, -14, v0
	s_nop 0
	v_cndmask_b32_e32 v215, v194, v215, vcc
	v_cmp_le_i32_e32 vcc, v3, v197
	v_subrev_u32_e32 v3, 45, v0
	s_nop 0
	v_cndmask_b32_e32 v231, v194, v231, vcc
	v_cmp_le_i32_e32 vcc, v3, v197
	v_add_u32_e32 v3, -13, v0
	s_nop 0
	v_cndmask_b32_e32 v216, v194, v216, vcc
	v_cmp_le_i32_e32 vcc, v3, v197
	v_subrev_u32_e32 v3, 44, v0
	s_nop 0
	v_cndmask_b32_e32 v232, v194, v232, vcc
	v_cmp_le_i32_e32 vcc, v3, v197
	v_add_u32_e32 v3, -12, v0
	s_nop 0
	v_cndmask_b32_e32 v217, v194, v217, vcc
	v_cmp_le_i32_e32 vcc, v3, v197
	v_subrev_u32_e32 v3, 39, v0
	s_nop 0
	v_cndmask_b32_e32 v233, v194, v233, vcc
	v_cmp_le_i32_e32 vcc, v3, v197
	v_add_u32_e32 v3, -7, v0
	s_nop 0
	v_cndmask_b32_e32 v218, v194, v218, vcc
	v_cmp_le_i32_e32 vcc, v3, v197
	v_subrev_u32_e32 v3, 38, v0
	s_nop 0
	v_cndmask_b32_e32 v234, v194, v234, vcc
	v_cmp_le_i32_e32 vcc, v3, v197
	v_add_u32_e32 v3, -6, v0
	s_nop 0
	v_cndmask_b32_e32 v219, v194, v219, vcc
	v_cmp_le_i32_e32 vcc, v3, v197
	v_subrev_u32_e32 v3, 37, v0
	s_nop 0
	v_cndmask_b32_e32 v235, v194, v235, vcc
	v_cmp_le_i32_e32 vcc, v3, v197
	v_add_u32_e32 v3, -5, v0
	s_nop 0
	v_cndmask_b32_e32 v220, v194, v220, vcc
	v_cmp_le_i32_e32 vcc, v3, v197
	v_subrev_u32_e32 v3, 36, v0
	v_add_u32_e32 v0, -4, v0
	v_cndmask_b32_e32 v236, v194, v236, vcc
	v_cmp_le_i32_e32 vcc, v3, v197
	s_nop 1
	v_cndmask_b32_e32 v221, v194, v221, vcc
	v_cmp_le_i32_e32 vcc, v0, v197
	s_nop 1
	v_cndmask_b32_e32 v237, v194, v237, vcc
.Lmaskdone_ba:
	s_mul_i32 s94, s93, 0x5000
	v_add_u32_e32 v4, s94, v203
	v_add_u32_e32 v5, 0xc800, v4
	ds_read_b64_tr_b16 v[238:239], v4 offset:51200
	ds_read_b64_tr_b16 v[240:241], v4 offset:53760
	ds_read_b64_tr_b16 v[244:245], v4 offset:51264
	ds_read_b64_tr_b16 v[246:247], v4 offset:53824
	ds_read_b64_tr_b16 v[248:249], v4 offset:51328
	ds_read_b64_tr_b16 v[250:251], v4 offset:53888
	ds_read_b64_tr_b16 v[8:9], v4 offset:51392
	ds_read_b64_tr_b16 v[10:11], v4 offset:53952
	ds_read_b64_tr_b16 v[12:13], v4 offset:56320
	ds_read_b64_tr_b16 v[14:15], v4 offset:58880
	s_waitcnt lgkmcnt(8)
	v_mfma_f32_32x32x16_bf16 v[64:79], v[96:99], v[238:241], v[64:79]
	ds_read_b64_tr_b16 v[238:239], v4 offset:56384
	ds_read_b64_tr_b16 v[240:241], v4 offset:58944
	s_waitcnt lgkmcnt(8)
	v_mfma_f32_32x32x16_bf16 v[48:63], v[96:99], v[244:247], v[48:63]
	ds_read_b64_tr_b16 v[244:245], v4 offset:56448
	ds_read_b64_tr_b16 v[246:247], v4 offset:59008
	s_waitcnt lgkmcnt(8)
	v_mfma_f32_32x32x16_bf16 v[32:47], v[96:99], v[248:251], v[32:47]
	ds_read_b64_tr_b16 v[248:249], v4 offset:56512
	ds_read_b64_tr_b16 v[250:251], v4 offset:59072
	s_waitcnt lgkmcnt(8)
	v_mfma_f32_32x32x16_bf16 v[16:31], v[96:99], v[8:11], v[16:31]
	ds_read_b64_tr_b16 v[8:9], v4 offset:61440
	ds_read_b64_tr_b16 v[10:11], v4 offset:64000
	v_max_f32_e32 v0, v206, v207
	v_max3_f32 v3, v208, v209, v223
	s_waitcnt lgkmcnt(8)
	v_mfma_f32_32x32x16_bf16 v[64:79], v[104:107], v[12:15], v[64:79]
	ds_read_b64_tr_b16 v[12:13], v4 offset:61504
	ds_read_b64_tr_b16 v[14:15], v4 offset:64064
	v_max3_f32 v0, v0, v222, v224
	v_max3_f32 v0, v0, v225, v210
	s_waitcnt lgkmcnt(8)
	v_mfma_f32_32x32x16_bf16 v[48:63], v[104:107], v[238:241], v[48:63]
	ds_read_b64_tr_b16 v[238:239], v4 offset:61568
	ds_read_b64_tr_b16 v[240:241], v4 offset:64128
	v_max3_f32 v3, v3, v212, v213
	s_waitcnt lgkmcnt(8)
	v_mfma_f32_32x32x16_bf16 v[32:47], v[104:107], v[244:247], v[32:47]
	ds_read_b64_tr_b16 v[244:245], v4 offset:61632
	ds_read_b64_tr_b16 v[246:247], v4 offset:64192
	v_max3_f32 v0, v0, v211, v226
	v_max3_f32 v3, v3, v228, v229
	s_waitcnt lgkmcnt(8)
	v_mfma_f32_32x32x16_bf16 v[16:31], v[104:107], v[248:251], v[16:31]
	ds_read_b64_tr_b16 v[248:249], v5 offset:15360
	ds_read_b64_tr_b16 v[250:251], v5 offset:17920
	v_max3_f32 v0, v0, v227, v214
	v_max3_f32 v3, v3, v216, v217
	s_waitcnt lgkmcnt(8)
	v_mfma_f32_32x32x16_bf16 v[64:79], v[112:115], v[8:11], v[64:79]
	ds_read_b64_tr_b16 v[8:9], v5 offset:15424
	ds_read_b64_tr_b16 v[10:11], v5 offset:17984
	v_max3_f32 v0, v0, v215, v230
	s_waitcnt lgkmcnt(8)
	v_mfma_f32_32x32x16_bf16 v[48:63], v[112:115], v[12:15], v[48:63]
	ds_read_b64_tr_b16 v[12:13], v5 offset:15488
	ds_read_b64_tr_b16 v[14:15], v5 offset:18048
	v_max3_f32 v3, v3, v232, v233
	v_max3_f32 v0, v0, v231, v218
	s_waitcnt lgkmcnt(8)
	v_mfma_f32_32x32x16_bf16 v[32:47], v[112:115], v[238:241], v[32:47]
	ds_read_b64_tr_b16 v[238:239], v5 offset:15552
	ds_read_b64_tr_b16 v[240:241], v5 offset:18112
	v_max3_f32 v3, v3, v220, v221
	v_max3_f32 v0, v0, v219, v234
	s_waitcnt lgkmcnt(8)
	v_mfma_f32_32x32x16_bf16 v[16:31], v[112:115], v[244:247], v[16:31]
	v_max3_f32 v3, v3, v236, v237
	s_waitcnt lgkmcnt(6)
	v_mfma_f32_32x32x16_bf16 v[64:79], v[120:123], v[248:251], v[64:79]
	v_max3_f32 v0, v0, v235, v3
	v_mov_b32_e32 v3, v0
	s_waitcnt lgkmcnt(4)
	v_mfma_f32_32x32x16_bf16 v[48:63], v[120:123], v[8:11], v[48:63]
	s_nop 1
	v_permlane32_swap_b32_e32 v0, v3
	s_waitcnt lgkmcnt(2)
	v_mfma_f32_32x32x16_bf16 v[32:47], v[120:123], v[12:15], v[32:47]
	v_max_f32_e32 v0, v0, v3
	s_waitcnt lgkmcnt(0)
	v_mfma_f32_32x32x16_bf16 v[16:31], v[120:123], v[238:241], v[16:31]
	s_cmp_lg_u32 s75, 63
	s_cselect_b64 s[60:61], -1, 0
	s_cmp_eq_u32 s75, 63
	s_mov_b64 s[62:63], -1
	s_cbranch_scc1 .LBB0_2161_ba
	v_cmp_lt_f32_e32 vcc, s31, v0
	s_cbranch_vccz .LBB0_2170_ba
	v_max_f32_e32 v0, v0, v0
	v_max_f32_e32 v0, 0, v0

.Lnovis_ba:
	s_sub_i32 s61, s75, 0x7f
	s_cmp_gt_i32 s61, s25
	s_cbranch_scc1 .Lend_ba
	s_mul_i32 s94, s93, 0x5000
	v_add_u32_e32 v4, s94, v203
	v_add_u32_e32 v5, 0xc800, v4
	ds_read_b64_tr_b16 v[238:239], v4 offset:51200
	ds_read_b64_tr_b16 v[240:241], v4 offset:53760
	ds_read_b64_tr_b16 v[244:245], v4 offset:51264
	ds_read_b64_tr_b16 v[246:247], v4 offset:53824
	ds_read_b64_tr_b16 v[248:249], v4 offset:51328
	ds_read_b64_tr_b16 v[250:251], v4 offset:53888
	ds_read_b64_tr_b16 v[8:9], v4 offset:51392
	ds_read_b64_tr_b16 v[10:11], v4 offset:53952
	ds_read_b64_tr_b16 v[12:13], v4 offset:56320
	ds_read_b64_tr_b16 v[14:15], v4 offset:58880
	v_exp_f32_e32 v96, v96
	v_exp_f32_e32 v97, v97
	v_exp_f32_e32 v98, v98
	v_exp_f32_e32 v99, v99
	v_exp_f32_e32 v100, v100
	v_exp_f32_e32 v101, v101
	v_exp_f32_e32 v102, v102
	v_exp_f32_e32 v103, v103
	v_add_f32_e32 v252, v96, v97
	v_add_f32_e32 v253, v98, v99
	v_add_f32_e32 v254, v100, v101
	v_add_f32_e32 v205, v102, v103
	s_nop 0
	v_cvt_pk_bf16_f32 v96, v96, v97
	v_cvt_pk_bf16_f32 v97, v98, v99
	v_cvt_pk_bf16_f32 v98, v100, v101
	v_cvt_pk_bf16_f32 v99, v102, v103
	s_nop 1
	s_waitcnt lgkmcnt(8)
	v_mfma_f32_32x32x16_bf16 v[64:79], v[96:99], v[238:241], v[64:79]
	ds_read_b64_tr_b16 v[238:239], v4 offset:56384
	ds_read_b64_tr_b16 v[240:241], v4 offset:58944
	v_exp_f32_e32 v104, v104
	v_exp_f32_e32 v105, v105
	v_exp_f32_e32 v106, v106
	v_exp_f32_e32 v107, v107
	v_exp_f32_e32 v108, v108
	v_exp_f32_e32 v109, v109
	s_waitcnt lgkmcnt(8)
	v_mfma_f32_32x32x16_bf16 v[48:63], v[96:99], v[244:247], v[48:63]
	ds_read_b64_tr_b16 v[244:245], v4 offset:56448
	ds_read_b64_tr_b16 v[246:247], v4 offset:59008
	v_exp_f32_e32 v110, v110
	v_exp_f32_e32 v111, v111
	v_add_f32_e32 v252, v252, v104
	v_add_f32_e32 v253, v253, v105
	v_add_f32_e32 v254, v254, v106
	s_waitcnt lgkmcnt(8)
	v_mfma_f32_32x32x16_bf16 v[32:47], v[96:99], v[248:251], v[32:47]
	ds_read_b64_tr_b16 v[248:249], v4 offset:56512
	ds_read_b64_tr_b16 v[250:251], v4 offset:59072
	v_add_f32_e32 v205, v205, v107
	v_add_f32_e32 v252, v252, v108
	v_add_f32_e32 v253, v253, v109
	v_add_f32_e32 v254, v254, v110
	v_add_f32_e32 v205, v205, v111
	s_waitcnt lgkmcnt(8)
	v_mfma_f32_32x32x16_bf16 v[16:31], v[96:99], v[8:11], v[16:31]
	ds_read_b64_tr_b16 v[8:9], v4 offset:61440
	ds_read_b64_tr_b16 v[10:11], v4 offset:64000
	v_cvt_pk_bf16_f32 v104, v104, v105
	v_cvt_pk_bf16_f32 v105, v106, v107
	v_cvt_pk_bf16_f32 v106, v108, v109
	v_cvt_pk_bf16_f32 v107, v110, v111
	s_nop 1
	s_waitcnt lgkmcnt(8)
	v_mfma_f32_32x32x16_bf16 v[64:79], v[104:107], v[12:15], v[64:79]
	ds_read_b64_tr_b16 v[12:13], v4 offset:61504
	ds_read_b64_tr_b16 v[14:15], v4 offset:64064
	v_exp_f32_e32 v112, v112
	v_exp_f32_e32 v113, v113
	v_exp_f32_e32 v114, v114
	v_exp_f32_e32 v115, v115
	v_exp_f32_e32 v116, v116
	v_exp_f32_e32 v117, v117
	s_waitcnt lgkmcnt(8)
	v_mfma_f32_32x32x16_bf16 v[48:63], v[104:107], v[238:241], v[48:63]
	ds_read_b64_tr_b16 v[238:239], v4 offset:61568
	ds_read_b64_tr_b16 v[240:241], v4 offset:64128
	v_exp_f32_e32 v118, v118
	v_exp_f32_e32 v119, v119
	v_add_f32_e32 v252, v252, v112
	v_add_f32_e32 v253, v253, v113
	v_add_f32_e32 v254, v254, v114
	s_waitcnt lgkmcnt(8)
	v_mfma_f32_32x32x16_bf16 v[32:47], v[104:107], v[244:247], v[32:47]
	ds_read_b64_tr_b16 v[244:245], v4 offset:61632
	ds_read_b64_tr_b16 v[246:247], v4 offset:64192
	v_add_f32_e32 v205, v205, v115
	v_add_f32_e32 v252, v252, v116
	v_add_f32_e32 v253, v253, v117
	v_add_f32_e32 v254, v254, v118
	v_add_f32_e32 v205, v205, v119
	s_waitcnt lgkmcnt(8)
	v_mfma_f32_32x32x16_bf16 v[16:31], v[104:107], v[248:251], v[16:31]
	ds_read_b64_tr_b16 v[248:249], v5 offset:15360
	ds_read_b64_tr_b16 v[250:251], v5 offset:17920
	v_cvt_pk_bf16_f32 v112, v112, v113
	v_cvt_pk_bf16_f32 v113, v114, v115
	v_cvt_pk_bf16_f32 v114, v116, v117
	v_cvt_pk_bf16_f32 v115, v118, v119
	s_nop 1
	s_waitcnt lgkmcnt(8)
	v_mfma_f32_32x32x16_bf16 v[64:79], v[112:115], v[8:11], v[64:79]
	ds_read_b64_tr_b16 v[8:9], v5 offset:15424
	ds_read_b64_tr_b16 v[10:11], v5 offset:17984
	v_exp_f32_e32 v120, v120
	v_exp_f32_e32 v121, v121
	v_exp_f32_e32 v122, v122
	v_exp_f32_e32 v123, v123
	v_exp_f32_e32 v124, v124
	v_exp_f32_e32 v125, v125
	s_waitcnt lgkmcnt(8)
	v_mfma_f32_32x32x16_bf16 v[48:63], v[112:115], v[12:15], v[48:63]
	ds_read_b64_tr_b16 v[12:13], v5 offset:15488
	ds_read_b64_tr_b16 v[14:15], v5 offset:18048
	v_exp_f32_e32 v126, v126
	v_exp_f32_e32 v127, v127
	v_add_f32_e32 v252, v252, v120
	v_add_f32_e32 v253, v253, v121
	v_add_f32_e32 v254, v254, v122
	s_waitcnt lgkmcnt(8)
	v_mfma_f32_32x32x16_bf16 v[32:47], v[112:115], v[238:241], v[32:47]
	ds_read_b64_tr_b16 v[238:239], v5 offset:15552
	ds_read_b64_tr_b16 v[240:241], v5 offset:18112
	v_add_f32_e32 v205, v205, v123
	v_add_f32_e32 v252, v252, v124
	v_add_f32_e32 v253, v253, v125
	v_add_f32_e32 v254, v254, v126
	v_add_f32_e32 v205, v205, v127
	s_waitcnt lgkmcnt(8)
	v_mfma_f32_32x32x16_bf16 v[16:31], v[112:115], v[244:247], v[16:31]
	v_cvt_pk_bf16_f32 v120, v120, v121
	v_cvt_pk_bf16_f32 v121, v122, v123
	v_cvt_pk_bf16_f32 v122, v124, v125
	v_cvt_pk_bf16_f32 v123, v126, v127
	s_nop 1
	s_waitcnt lgkmcnt(6)
	v_mfma_f32_32x32x16_bf16 v[64:79], v[120:123], v[248:251], v[64:79]
	v_add_f32_e32 v252, v252, v253
	s_waitcnt lgkmcnt(4)
	v_mfma_f32_32x32x16_bf16 v[48:63], v[120:123], v[8:11], v[48:63]
	v_add_f32_e32 v254, v254, v205
	s_waitcnt lgkmcnt(2)
	v_mfma_f32_32x32x16_bf16 v[32:47], v[120:123], v[12:15], v[32:47]
	v_add_f32_e32 v252, v252, v254
	s_waitcnt lgkmcnt(0)
	v_mfma_f32_32x32x16_bf16 v[16:31], v[120:123], v[238:241], v[16:31]
	v_add_f32_e32 v2, v2, v252

.Lskip_v2_2_ab:
.LBB0_2155_ab:
	s_sub_i32 s61, s75, 63
	s_cmp_gt_i32 s61, s25
	s_cbranch_scc1 .Lnovis_ab
	s_bitcmp1_b32 s60, 0
	s_cselect_b32 s60, 0x6400, 0
	v_add_u32_e32 v0, s60, v200
	ds_read_b128 v[238:241], v0
	ds_read_b128 v[244:247], v0 offset:32
	ds_read_b128 v[248:251], v0 offset:12800
	ds_read_b128 v[8:11], v0 offset:12832
	ds_read_b128 v[12:15], v0 offset:64
	s_waitcnt lgkmcnt(4)
	v_mfma_f32_32x32x16_bf16 v[96:111], v[238:241], v[128:131], v[80:95]
	ds_read_b128 v[238:241], v0 offset:12864
	v_exp_f32_e32 v206, v206
	v_exp_f32_e32 v207, v207
	v_exp_f32_e32 v208, v208
	v_exp_f32_e32 v209, v209
	s_waitcnt lgkmcnt(4)
	v_mfma_f32_32x32x16_bf16 v[96:111], v[244:247], v[132:135], v[96:111]
	ds_read_b128 v[244:247], v0 offset:96
	v_exp_f32_e32 v210, v210
	v_exp_f32_e32 v211, v211
	v_exp_f32_e32 v212, v212
	s_waitcnt lgkmcnt(4)
	v_mfma_f32_32x32x16_bf16 v[112:127], v[248:251], v[128:131], v[80:95]
	ds_read_b128 v[248:251], v0 offset:12896
	v_exp_f32_e32 v213, v213
	v_exp_f32_e32 v214, v214
	v_exp_f32_e32 v215, v215
	s_waitcnt lgkmcnt(4)
	v_mfma_f32_32x32x16_bf16 v[112:127], v[8:11], v[132:135], v[112:127]
	ds_read_b128 v[8:11], v0 offset:128
	v_exp_f32_e32 v216, v216
	v_exp_f32_e32 v217, v217
	v_exp_f32_e32 v218, v218
	v_exp_f32_e32 v219, v219
	s_waitcnt lgkmcnt(4)
	v_mfma_f32_32x32x16_bf16 v[96:111], v[12:15], v[136:139], v[96:111]
	ds_read_b128 v[12:15], v0 offset:12928
	v_exp_f32_e32 v220, v220
	v_exp_f32_e32 v221, v221
	v_add_f32_e32 v252, v206, v207
	s_waitcnt lgkmcnt(4)
	v_mfma_f32_32x32x16_bf16 v[112:127], v[238:241], v[136:139], v[112:127]
	ds_read_b128 v[238:241], v0 offset:160
	v_add_f32_e32 v253, v208, v209
	v_add_f32_e32 v254, v210, v211
	v_add_f32_e32 v205, v212, v213
	s_waitcnt lgkmcnt(4)
	v_mfma_f32_32x32x16_bf16 v[96:111], v[244:247], v[140:143], v[96:111]
	ds_read_b128 v[244:247], v0 offset:12960
	v_cvt_pk_bf16_f32 v206, v206, v207
	v_cvt_pk_bf16_f32 v207, v208, v209
	v_cvt_pk_bf16_f32 v208, v210, v211
	v_cvt_pk_bf16_f32 v209, v212, v213
	s_waitcnt lgkmcnt(4)
	v_mfma_f32_32x32x16_bf16 v[112:127], v[248:251], v[140:143], v[112:127]
	ds_read_b128 v[248:251], v0 offset:192
	v_exp_f32_e32 v222, v222
	v_exp_f32_e32 v223, v223
	v_exp_f32_e32 v224, v224
	s_waitcnt lgkmcnt(4)
	v_mfma_f32_32x32x16_bf16 v[96:111], v[8:11], v[144:147], v[96:111]
	ds_read_b128 v[8:11], v0 offset:12992
	v_exp_f32_e32 v225, v225
	v_exp_f32_e32 v226, v226
	v_exp_f32_e32 v227, v227
	s_waitcnt lgkmcnt(4)
	v_mfma_f32_32x32x16_bf16 v[112:127], v[12:15], v[144:147], v[112:127]
	ds_read_b128 v[12:15], v0 offset:224
	v_exp_f32_e32 v228, v228
	v_exp_f32_e32 v229, v229
	v_add_f32_e32 v252, v252, v214
	v_add_f32_e32 v253, v253, v215
	s_waitcnt lgkmcnt(4)
	v_mfma_f32_32x32x16_bf16 v[96:111], v[238:241], v[148:151], v[96:111]
	ds_read_b128 v[238:241], v0 offset:13024
	v_add_f32_e32 v254, v254, v216
	v_add_f32_e32 v205, v205, v217
	v_add_f32_e32 v252, v252, v218
	s_waitcnt lgkmcnt(4)
	v_mfma_f32_32x32x16_bf16 v[112:127], v[244:247], v[148:151], v[112:127]
	ds_read_b128 v[244:247], v0 offset:256
	v_add_f32_e32 v253, v253, v219
	v_add_f32_e32 v254, v254, v220
	v_add_f32_e32 v205, v205, v221
	s_waitcnt lgkmcnt(4)
	v_mfma_f32_32x32x16_bf16 v[96:111], v[248:251], v[152:155], v[96:111]
	ds_read_b128 v[248:251], v0 offset:13056
	v_cvt_pk_bf16_f32 v214, v214, v215
	v_cvt_pk_bf16_f32 v215, v216, v217
	v_cvt_pk_bf16_f32 v216, v218, v219
	v_cvt_pk_bf16_f32 v217, v220, v221
	s_waitcnt lgkmcnt(4)
	v_mfma_f32_32x32x16_bf16 v[112:127], v[8:11], v[152:155], v[112:127]
	ds_read_b128 v[8:11], v0 offset:288
	v_exp_f32_e32 v230, v230
	v_exp_f32_e32 v231, v231
	v_exp_f32_e32 v232, v232
	s_waitcnt lgkmcnt(4)
	v_mfma_f32_32x32x16_bf16 v[96:111], v[12:15], v[156:159], v[96:111]
	ds_read_b128 v[12:15], v0 offset:13088
	v_exp_f32_e32 v233, v233
	v_exp_f32_e32 v234, v234
	v_exp_f32_e32 v235, v235
	s_waitcnt lgkmcnt(4)
	v_mfma_f32_32x32x16_bf16 v[112:127], v[238:241], v[156:159], v[112:127]
	ds_read_b128 v[238:241], v0 offset:320
	v_exp_f32_e32 v236, v236
	v_exp_f32_e32 v237, v237
	v_add_f32_e32 v252, v252, v222
	v_add_f32_e32 v253, v253, v223
	s_waitcnt lgkmcnt(4)
	v_mfma_f32_32x32x16_bf16 v[96:111], v[244:247], v[160:163], v[96:111]
	ds_read_b128 v[244:247], v0 offset:13120
	v_add_f32_e32 v254, v254, v224
	v_add_f32_e32 v205, v205, v225
	v_add_f32_e32 v252, v252, v226
	s_waitcnt lgkmcnt(4)
	v_mfma_f32_32x32x16_bf16 v[112:127], v[248:251], v[160:163], v[112:127]
	ds_read_b128 v[248:251], v0 offset:352
	v_add_f32_e32 v253, v253, v227
	v_add_f32_e32 v254, v254, v228
	v_add_f32_e32 v205, v205, v229
	s_waitcnt lgkmcnt(4)
	v_mfma_f32_32x32x16_bf16 v[96:111], v[8:11], v[164:167], v[96:111]
	ds_read_b128 v[8:11], v0 offset:13152
	v_cvt_pk_bf16_f32 v222, v222, v223
	v_cvt_pk_bf16_f32 v223, v224, v225
	v_cvt_pk_bf16_f32 v224, v226, v227
	v_cvt_pk_bf16_f32 v225, v228, v229
	s_waitcnt lgkmcnt(4)
	v_mfma_f32_32x32x16_bf16 v[112:127], v[12:15], v[164:167], v[112:127]
	v_add_f32_e32 v252, v252, v230
	v_add_f32_e32 v253, v253, v231
	v_add_f32_e32 v254, v254, v232
	s_waitcnt lgkmcnt(3)
	v_mfma_f32_32x32x16_bf16 v[96:111], v[238:241], v[168:171], v[96:111]
	v_add_f32_e32 v205, v205, v233
	v_add_f32_e32 v252, v252, v234
	v_add_f32_e32 v253, v253, v235
	s_waitcnt lgkmcnt(2)
	v_mfma_f32_32x32x16_bf16 v[112:127], v[244:247], v[168:171], v[112:127]
	v_add_f32_e32 v254, v254, v236
	v_add_f32_e32 v205, v205, v237
	v_cvt_pk_bf16_f32 v230, v230, v231
	v_cvt_pk_bf16_f32 v231, v232, v233
	s_waitcnt lgkmcnt(1)
	v_mfma_f32_32x32x16_bf16 v[96:111], v[248:251], v[172:175], v[96:111]
	v_cvt_pk_bf16_f32 v232, v234, v235
	v_cvt_pk_bf16_f32 v233, v236, v237
	v_add_f32_e32 v252, v252, v253
	s_waitcnt lgkmcnt(0)
	v_mfma_f32_32x32x16_bf16 v[112:127], v[8:11], v[172:175], v[112:127]
	v_add_f32_e32 v254, v254, v205
	v_add_f32_e32 v252, v252, v254
	v_add_f32_e32 v2, v2, v252
	s_cmp_le_i32 s75, s68
	s_cbranch_scc1 .Lmaskdone_ab
	v_add_u32_e32 v0, s75, v201
	v_subrev_u32_e32 v4, 31, v0
	v_subrev_u32_e32 v3, 63, v0
	v_cmp_le_i32_e32 vcc, v4, v197
	s_nop 4
	v_cndmask_b32_e32 v112, v194, v112, vcc
	v_cmp_lt_i32_e32 vcc, v3, v197
	s_nop 1
	v_cndmask_b32_e32 v97, v194, v97, vcc
	v_cmp_le_i32_e32 vcc, v3, v197
	v_subrev_u32_e32 v3, 30, v0
	s_nop 0
	v_cndmask_b32_e32 v96, v194, v96, vcc
	v_cmp_le_i32_e32 vcc, v3, v197
	v_subrev_u32_e32 v3, 61, v0
	s_nop 0
	v_cndmask_b32_e32 v113, v194, v113, vcc
	v_cmp_le_i32_e32 vcc, v3, v197
	v_subrev_u32_e32 v3, 29, v0
	s_nop 0
	v_cndmask_b32_e32 v98, v194, v98, vcc
	v_cmp_le_i32_e32 vcc, v3, v197
	v_subrev_u32_e32 v3, 60, v0
	s_nop 0
	v_cndmask_b32_e32 v114, v194, v114, vcc
	v_cmp_le_i32_e32 vcc, v3, v197
	v_subrev_u32_e32 v3, 28, v0
	s_nop 0
	v_cndmask_b32_e32 v99, v194, v99, vcc
	v_cmp_le_i32_e32 vcc, v3, v197
	v_subrev_u32_e32 v3, 55, v0
	s_nop 0
	v_cndmask_b32_e32 v115, v194, v115, vcc
	v_cmp_le_i32_e32 vcc, v3, v197
	v_subrev_u32_e32 v3, 23, v0
	s_nop 0
	v_cndmask_b32_e32 v100, v194, v100, vcc
	v_cmp_le_i32_e32 vcc, v3, v197
	v_subrev_u32_e32 v3, 54, v0
	s_nop 0
	v_cndmask_b32_e32 v116, v194, v116, vcc
	v_cmp_le_i32_e32 vcc, v3, v197
	v_subrev_u32_e32 v3, 22, v0
	s_nop 0
	v_cndmask_b32_e32 v101, v194, v101, vcc
	v_cmp_le_i32_e32 vcc, v3, v197
	v_subrev_u32_e32 v3, 53, v0
	s_nop 0
	v_cndmask_b32_e32 v117, v194, v117, vcc
	v_cmp_le_i32_e32 vcc, v3, v197
	v_subrev_u32_e32 v3, 21, v0
	s_nop 0
	v_cndmask_b32_e32 v102, v194, v102, vcc
	v_cmp_le_i32_e32 vcc, v3, v197
	v_subrev_u32_e32 v3, 52, v0
	s_nop 0
	v_cndmask_b32_e32 v118, v194, v118, vcc
	v_cmp_le_i32_e32 vcc, v3, v197
	v_subrev_u32_e32 v3, 20, v0
	s_nop 0
	v_cndmask_b32_e32 v103, v194, v103, vcc
	v_cmp_le_i32_e32 vcc, v3, v197
	v_subrev_u32_e32 v3, 47, v0
	s_nop 0
	v_cndmask_b32_e32 v119, v194, v119, vcc
	v_cmp_le_i32_e32 vcc, v3, v197
	v_add_u32_e32 v3, -15, v0
	s_nop 0
	v_cndmask_b32_e32 v104, v194, v104, vcc
	v_cmp_le_i32_e32 vcc, v3, v197
	v_subrev_u32_e32 v3, 46, v0
	s_nop 0
	v_cndmask_b32_e32 v120, v194, v120, vcc
	v_cmp_le_i32_e32 vcc, v3, v197
	v_add_u32_e32 v3, -14, v0
	s_nop 0
	v_cndmask_b32_e32 v105, v194, v105, vcc
	v_cmp_le_i32_e32 vcc, v3, v197
	v_subrev_u32_e32 v3, 45, v0
	s_nop 0
	v_cndmask_b32_e32 v121, v194, v121, vcc
	v_cmp_le_i32_e32 vcc, v3, v197
	v_add_u32_e32 v3, -13, v0
	s_nop 0
	v_cndmask_b32_e32 v106, v194, v106, vcc
	v_cmp_le_i32_e32 vcc, v3, v197
	v_subrev_u32_e32 v3, 44, v0
	s_nop 0
	v_cndmask_b32_e32 v122, v194, v122, vcc
	v_cmp_le_i32_e32 vcc, v3, v197
	v_add_u32_e32 v3, -12, v0
	s_nop 0
	v_cndmask_b32_e32 v107, v194, v107, vcc
	v_cmp_le_i32_e32 vcc, v3, v197
	v_subrev_u32_e32 v3, 39, v0
	s_nop 0
	v_cndmask_b32_e32 v123, v194, v123, vcc
	v_cmp_le_i32_e32 vcc, v3, v197
	v_add_u32_e32 v3, -7, v0
	s_nop 0
	v_cndmask_b32_e32 v108, v194, v108, vcc
	v_cmp_le_i32_e32 vcc, v3, v197
	v_subrev_u32_e32 v3, 38, v0
	s_nop 0
	v_cndmask_b32_e32 v124, v194, v124, vcc
	v_cmp_le_i32_e32 vcc, v3, v197
	v_add_u32_e32 v3, -6, v0
	s_nop 0
	v_cndmask_b32_e32 v109, v194, v109, vcc
	v_cmp_le_i32_e32 vcc, v3, v197
	v_subrev_u32_e32 v3, 37, v0
	s_nop 0
	v_cndmask_b32_e32 v125, v194, v125, vcc
	v_cmp_le_i32_e32 vcc, v3, v197
	v_add_u32_e32 v3, -5, v0
	s_nop 0
	v_cndmask_b32_e32 v110, v194, v110, vcc
	v_cmp_le_i32_e32 vcc, v3, v197
	v_subrev_u32_e32 v3, 36, v0
	v_add_u32_e32 v0, -4, v0
	v_cndmask_b32_e32 v126, v194, v126, vcc
	v_cmp_le_i32_e32 vcc, v3, v197
	s_nop 1
	v_cndmask_b32_e32 v111, v194, v111, vcc
	v_cmp_le_i32_e32 vcc, v0, v197
	s_nop 1
	v_cndmask_b32_e32 v127, v194, v127, vcc
.Lmaskdone_ab:
	s_mul_i32 s94, s93, 0x5000
	v_add_u32_e32 v4, s94, v203
	v_add_u32_e32 v5, 0xc800, v4
	ds_read_b64_tr_b16 v[238:239], v4 offset:51200
	ds_read_b64_tr_b16 v[240:241], v4 offset:53760
	ds_read_b64_tr_b16 v[244:245], v4 offset:51264
	ds_read_b64_tr_b16 v[246:247], v4 offset:53824
	ds_read_b64_tr_b16 v[248:249], v4 offset:51328
	ds_read_b64_tr_b16 v[250:251], v4 offset:53888
	ds_read_b64_tr_b16 v[8:9], v4 offset:51392
	ds_read_b64_tr_b16 v[10:11], v4 offset:53952
	ds_read_b64_tr_b16 v[12:13], v4 offset:56320
	ds_read_b64_tr_b16 v[14:15], v4 offset:58880
	s_waitcnt lgkmcnt(8)
	v_mfma_f32_32x32x16_bf16 v[64:79], v[206:209], v[238:241], v[64:79]
	ds_read_b64_tr_b16 v[238:239], v4 offset:56384
	ds_read_b64_tr_b16 v[240:241], v4 offset:58944
	s_waitcnt lgkmcnt(8)
	v_mfma_f32_32x32x16_bf16 v[48:63], v[206:209], v[244:247], v[48:63]
	ds_read_b64_tr_b16 v[244:245], v4 offset:56448
	ds_read_b64_tr_b16 v[246:247], v4 offset:59008
	s_waitcnt lgkmcnt(8)
	v_mfma_f32_32x32x16_bf16 v[32:47], v[206:209], v[248:251], v[32:47]
	ds_read_b64_tr_b16 v[248:249], v4 offset:56512
	ds_read_b64_tr_b16 v[250:251], v4 offset:59072
	s_waitcnt lgkmcnt(8)
	v_mfma_f32_32x32x16_bf16 v[16:31], v[206:209], v[8:11], v[16:31]
	ds_read_b64_tr_b16 v[8:9], v4 offset:61440
	ds_read_b64_tr_b16 v[10:11], v4 offset:64000
	v_max_f32_e32 v0, v96, v97
	v_max3_f32 v3, v98, v99, v113
	s_waitcnt lgkmcnt(8)
	v_mfma_f32_32x32x16_bf16 v[64:79], v[214:217], v[12:15], v[64:79]
	ds_read_b64_tr_b16 v[12:13], v4 offset:61504
	ds_read_b64_tr_b16 v[14:15], v4 offset:64064
	v_max3_f32 v0, v0, v112, v114
	v_max3_f32 v0, v0, v115, v100
	s_waitcnt lgkmcnt(8)
	v_mfma_f32_32x32x16_bf16 v[48:63], v[214:217], v[238:241], v[48:63]
	ds_read_b64_tr_b16 v[238:239], v4 offset:61568
	ds_read_b64_tr_b16 v[240:241], v4 offset:64128
	v_max3_f32 v3, v3, v102, v103
	s_waitcnt lgkmcnt(8)
	v_mfma_f32_32x32x16_bf16 v[32:47], v[214:217], v[244:247], v[32:47]
	ds_read_b64_tr_b16 v[244:245], v4 offset:61632
	ds_read_b64_tr_b16 v[246:247], v4 offset:64192
	v_max3_f32 v0, v0, v101, v116
	v_max3_f32 v3, v3, v118, v119
	s_waitcnt lgkmcnt(8)
	v_mfma_f32_32x32x16_bf16 v[16:31], v[214:217], v[248:251], v[16:31]
	ds_read_b64_tr_b16 v[248:249], v5 offset:15360
	ds_read_b64_tr_b16 v[250:251], v5 offset:17920
	v_max3_f32 v0, v0, v117, v104
	v_max3_f32 v3, v3, v106, v107
	s_waitcnt lgkmcnt(8)
	v_mfma_f32_32x32x16_bf16 v[64:79], v[222:225], v[8:11], v[64:79]
	ds_read_b64_tr_b16 v[8:9], v5 offset:15424
	ds_read_b64_tr_b16 v[10:11], v5 offset:17984
	v_max3_f32 v0, v0, v105, v120
	s_waitcnt lgkmcnt(8)
	v_mfma_f32_32x32x16_bf16 v[48:63], v[222:225], v[12:15], v[48:63]
	ds_read_b64_tr_b16 v[12:13], v5 offset:15488
	ds_read_b64_tr_b16 v[14:15], v5 offset:18048
	v_max3_f32 v3, v3, v122, v123
	v_max3_f32 v0, v0, v121, v108
	s_waitcnt lgkmcnt(8)
	v_mfma_f32_32x32x16_bf16 v[32:47], v[222:225], v[238:241], v[32:47]
	ds_read_b64_tr_b16 v[238:239], v5 offset:15552
	ds_read_b64_tr_b16 v[240:241], v5 offset:18112
	v_max3_f32 v3, v3, v110, v111
	v_max3_f32 v0, v0, v109, v124
	s_waitcnt lgkmcnt(8)
	v_mfma_f32_32x32x16_bf16 v[16:31], v[222:225], v[244:247], v[16:31]
	v_max3_f32 v3, v3, v126, v127
	s_waitcnt lgkmcnt(6)
	v_mfma_f32_32x32x16_bf16 v[64:79], v[230:233], v[248:251], v[64:79]
	v_max3_f32 v0, v0, v125, v3
	v_mov_b32_e32 v3, v0
	s_waitcnt lgkmcnt(4)
	v_mfma_f32_32x32x16_bf16 v[48:63], v[230:233], v[8:11], v[48:63]
	s_nop 1
	v_permlane32_swap_b32_e32 v0, v3
	s_waitcnt lgkmcnt(2)
	v_mfma_f32_32x32x16_bf16 v[32:47], v[230:233], v[12:15], v[32:47]
	v_max_f32_e32 v0, v0, v3
	s_waitcnt lgkmcnt(0)
	v_mfma_f32_32x32x16_bf16 v[16:31], v[230:233], v[238:241], v[16:31]
	s_cmp_lg_u32 s75, 63
	s_cselect_b64 s[60:61], -1, 0
	s_cmp_eq_u32 s75, 63
	s_mov_b64 s[62:63], -1
	s_cbranch_scc1 .LBB0_2161_ab
	v_cmp_lt_f32_e32 vcc, s31, v0
	s_cbranch_vccz .LBB0_2170_ab
	v_max_f32_e32 v0, v0, v0
	v_max_f32_e32 v0, 0, v0

.Lnovis_ab:
	s_sub_i32 s61, s75, 0x7f
	s_cmp_gt_i32 s61, s25
	s_cbranch_scc1 .Lend_ab
	s_mul_i32 s94, s93, 0x5000
	v_add_u32_e32 v4, s94, v203
	v_add_u32_e32 v5, 0xc800, v4
	ds_read_b64_tr_b16 v[238:239], v4 offset:51200
	ds_read_b64_tr_b16 v[240:241], v4 offset:53760
	ds_read_b64_tr_b16 v[244:245], v4 offset:51264
	ds_read_b64_tr_b16 v[246:247], v4 offset:53824
	ds_read_b64_tr_b16 v[248:249], v4 offset:51328
	ds_read_b64_tr_b16 v[250:251], v4 offset:53888
	ds_read_b64_tr_b16 v[8:9], v4 offset:51392
	ds_read_b64_tr_b16 v[10:11], v4 offset:53952
	ds_read_b64_tr_b16 v[12:13], v4 offset:56320
	ds_read_b64_tr_b16 v[14:15], v4 offset:58880
	v_exp_f32_e32 v206, v206
	v_exp_f32_e32 v207, v207
	v_exp_f32_e32 v208, v208
	v_exp_f32_e32 v209, v209
	v_exp_f32_e32 v210, v210
	v_exp_f32_e32 v211, v211
	v_exp_f32_e32 v212, v212
	v_exp_f32_e32 v213, v213
	v_add_f32_e32 v252, v206, v207
	v_add_f32_e32 v253, v208, v209
	v_add_f32_e32 v254, v210, v211
	v_add_f32_e32 v205, v212, v213
	s_nop 0
	v_cvt_pk_bf16_f32 v206, v206, v207
	v_cvt_pk_bf16_f32 v207, v208, v209
	v_cvt_pk_bf16_f32 v208, v210, v211
	v_cvt_pk_bf16_f32 v209, v212, v213
	s_nop 1
	s_waitcnt lgkmcnt(8)
	v_mfma_f32_32x32x16_bf16 v[64:79], v[206:209], v[238:241], v[64:79]
	ds_read_b64_tr_b16 v[238:239], v4 offset:56384
	ds_read_b64_tr_b16 v[240:241], v4 offset:58944
	v_exp_f32_e32 v214, v214
	v_exp_f32_e32 v215, v215
	v_exp_f32_e32 v216, v216
	v_exp_f32_e32 v217, v217
	v_exp_f32_e32 v218, v218
	v_exp_f32_e32 v219, v219
	s_waitcnt lgkmcnt(8)
	v_mfma_f32_32x32x16_bf16 v[48:63], v[206:209], v[244:247], v[48:63]
	ds_read_b64_tr_b16 v[244:245], v4 offset:56448
	ds_read_b64_tr_b16 v[246:247], v4 offset:59008
	v_exp_f32_e32 v220, v220
	v_exp_f32_e32 v221, v221
	v_add_f32_e32 v252, v252, v214
	v_add_f32_e32 v253, v253, v215
	v_add_f32_e32 v254, v254, v216
	s_waitcnt lgkmcnt(8)
	v_mfma_f32_32x32x16_bf16 v[32:47], v[206:209], v[248:251], v[32:47]
	ds_read_b64_tr_b16 v[248:249], v4 offset:56512
	ds_read_b64_tr_b16 v[250:251], v4 offset:59072
	v_add_f32_e32 v205, v205, v217
	v_add_f32_e32 v252, v252, v218
	v_add_f32_e32 v253, v253, v219
	v_add_f32_e32 v254, v254, v220
	v_add_f32_e32 v205, v205, v221
	s_waitcnt lgkmcnt(8)
	v_mfma_f32_32x32x16_bf16 v[16:31], v[206:209], v[8:11], v[16:31]
	ds_read_b64_tr_b16 v[8:9], v4 offset:61440
	ds_read_b64_tr_b16 v[10:11], v4 offset:64000
	v_cvt_pk_bf16_f32 v214, v214, v215
	v_cvt_pk_bf16_f32 v215, v216, v217
	v_cvt_pk_bf16_f32 v216, v218, v219
	v_cvt_pk_bf16_f32 v217, v220, v221
	s_nop 1
	s_waitcnt lgkmcnt(8)
	v_mfma_f32_32x32x16_bf16 v[64:79], v[214:217], v[12:15], v[64:79]
	ds_read_b64_tr_b16 v[12:13], v4 offset:61504
	ds_read_b64_tr_b16 v[14:15], v4 offset:64064
	v_exp_f32_e32 v222, v222
	v_exp_f32_e32 v223, v223
	v_exp_f32_e32 v224, v224
	v_exp_f32_e32 v225, v225
	v_exp_f32_e32 v226, v226
	v_exp_f32_e32 v227, v227
	s_waitcnt lgkmcnt(8)
	v_mfma_f32_32x32x16_bf16 v[48:63], v[214:217], v[238:241], v[48:63]
	ds_read_b64_tr_b16 v[238:239], v4 offset:61568
	ds_read_b64_tr_b16 v[240:241], v4 offset:64128
	v_exp_f32_e32 v228, v228
	v_exp_f32_e32 v229, v229
	v_add_f32_e32 v252, v252, v222
	v_add_f32_e32 v253, v253, v223
	v_add_f32_e32 v254, v254, v224
	s_waitcnt lgkmcnt(8)
	v_mfma_f32_32x32x16_bf16 v[32:47], v[214:217], v[244:247], v[32:47]
	ds_read_b64_tr_b16 v[244:245], v4 offset:61632
	ds_read_b64_tr_b16 v[246:247], v4 offset:64192
	v_add_f32_e32 v205, v205, v225
	v_add_f32_e32 v252, v252, v226
	v_add_f32_e32 v253, v253, v227
	v_add_f32_e32 v254, v254, v228
	v_add_f32_e32 v205, v205, v229
	s_waitcnt lgkmcnt(8)
	v_mfma_f32_32x32x16_bf16 v[16:31], v[214:217], v[248:251], v[16:31]
	ds_read_b64_tr_b16 v[248:249], v5 offset:15360
	ds_read_b64_tr_b16 v[250:251], v5 offset:17920
	v_cvt_pk_bf16_f32 v222, v222, v223
	v_cvt_pk_bf16_f32 v223, v224, v225
	v_cvt_pk_bf16_f32 v224, v226, v227
	v_cvt_pk_bf16_f32 v225, v228, v229
	s_nop 1
	s_waitcnt lgkmcnt(8)
	v_mfma_f32_32x32x16_bf16 v[64:79], v[222:225], v[8:11], v[64:79]
	ds_read_b64_tr_b16 v[8:9], v5 offset:15424
	ds_read_b64_tr_b16 v[10:11], v5 offset:17984
	v_exp_f32_e32 v230, v230
	v_exp_f32_e32 v231, v231
	v_exp_f32_e32 v232, v232
	v_exp_f32_e32 v233, v233
	v_exp_f32_e32 v234, v234
	v_exp_f32_e32 v235, v235
	s_waitcnt lgkmcnt(8)
	v_mfma_f32_32x32x16_bf16 v[48:63], v[222:225], v[12:15], v[48:63]
	ds_read_b64_tr_b16 v[12:13], v5 offset:15488
	ds_read_b64_tr_b16 v[14:15], v5 offset:18048
	v_exp_f32_e32 v236, v236
	v_exp_f32_e32 v237, v237
	v_add_f32_e32 v252, v252, v230
	v_add_f32_e32 v253, v253, v231
	v_add_f32_e32 v254, v254, v232
	s_waitcnt lgkmcnt(8)
	v_mfma_f32_32x32x16_bf16 v[32:47], v[222:225], v[238:241], v[32:47]
	ds_read_b64_tr_b16 v[238:239], v5 offset:15552
	ds_read_b64_tr_b16 v[240:241], v5 offset:18112
	v_add_f32_e32 v205, v205, v233
	v_add_f32_e32 v252, v252, v234
	v_add_f32_e32 v253, v253, v235
	v_add_f32_e32 v254, v254, v236
	v_add_f32_e32 v205, v205, v237
	s_waitcnt lgkmcnt(8)
	v_mfma_f32_32x32x16_bf16 v[16:31], v[222:225], v[244:247], v[16:31]
	v_cvt_pk_bf16_f32 v230, v230, v231
	v_cvt_pk_bf16_f32 v231, v232, v233
	v_cvt_pk_bf16_f32 v232, v234, v235
	v_cvt_pk_bf16_f32 v233, v236, v237
	s_nop 1
	s_waitcnt lgkmcnt(6)
	v_mfma_f32_32x32x16_bf16 v[64:79], v[230:233], v[248:251], v[64:79]
	v_add_f32_e32 v252, v252, v253
	s_waitcnt lgkmcnt(4)
	v_mfma_f32_32x32x16_bf16 v[48:63], v[230:233], v[8:11], v[48:63]
	v_add_f32_e32 v254, v254, v205
	s_waitcnt lgkmcnt(2)
	v_mfma_f32_32x32x16_bf16 v[32:47], v[230:233], v[12:15], v[32:47]
	v_add_f32_e32 v252, v252, v254
	s_waitcnt lgkmcnt(0)
	v_mfma_f32_32x32x16_bf16 v[16:31], v[230:233], v[238:241], v[16:31]
	v_add_f32_e32 v2, v2, v252

; template <int DQK>
; __device__ __forceinline__ void attn_pass4(LAS unsigned char* lds, const bf16* Qp, int qpitch, const bf16* Kp, int kpitch, const bf16* Vp, int vpitch, int q0, f32x16 (&o)[4], float (&rl)[16]) {
;     ...
;         if (ATT_VIS(NT - 1)) ATT_B(vprev);
.Lend_fin:
	s_add_i32 s75, s75, 64
	s_add_u32 s58, s58, 0x20000
	s_addc_u32 s59, s59, 0
	s_add_u32 s56, s56, 0x30000
	s_waitcnt vmcnt(0) lgkmcnt(0)
	s_barrier
	s_addc_u32 s57, s57, 0
	s_cmp_eq_u32 s69, s77
	s_mov_b32 s93, s78
	s_mov_b32 s78, s76
	s_mov_b32 s60, s77
	s_sub_i32 s61, s75, 0x7f
	s_cmp_gt_i32 s61, s25
	s_cbranch_scc1 .Lpipe_done
	s_mul_i32 s94, s93, 0x5000
	v_add_u32_e32 v4, s94, v203
	v_add_u32_e32 v5, 0xc800, v4
	ds_read_b64_tr_b16 v[238:239], v4 offset:51200
	ds_read_b64_tr_b16 v[240:241], v4 offset:53760
	ds_read_b64_tr_b16 v[244:245], v4 offset:51264
	ds_read_b64_tr_b16 v[246:247], v4 offset:53824
	ds_read_b64_tr_b16 v[248:249], v4 offset:51328
	ds_read_b64_tr_b16 v[250:251], v4 offset:53888
	ds_read_b64_tr_b16 v[8:9], v4 offset:51392
	ds_read_b64_tr_b16 v[10:11], v4 offset:53952
	ds_read_b64_tr_b16 v[12:13], v4 offset:56320
	ds_read_b64_tr_b16 v[14:15], v4 offset:58880
	v_exp_f32_e32 v206, v206
	v_exp_f32_e32 v207, v207
	v_exp_f32_e32 v208, v208
	v_exp_f32_e32 v209, v209
	v_exp_f32_e32 v210, v210
	v_exp_f32_e32 v211, v211
	v_exp_f32_e32 v212, v212
	v_exp_f32_e32 v213, v213
	v_add_f32_e32 v252, v206, v207
	v_add_f32_e32 v253, v208, v209
	v_add_f32_e32 v254, v210, v211
	v_add_f32_e32 v205, v212, v213
	s_nop 0
	v_cvt_pk_bf16_f32 v206, v206, v207
	v_cvt_pk_bf16_f32 v207, v208, v209
	v_cvt_pk_bf16_f32 v208, v210, v211
	v_cvt_pk_bf16_f32 v209, v212, v213
	s_nop 1
	s_waitcnt lgkmcnt(8)
	v_mfma_f32_32x32x16_bf16 v[64:79], v[206:209], v[238:241], v[64:79]
	ds_read_b64_tr_b16 v[238:239], v4 offset:56384
	ds_read_b64_tr_b16 v[240:241], v4 offset:58944
	v_exp_f32_e32 v214, v214
	v_exp_f32_e32 v215, v215
	v_exp_f32_e32 v216, v216
	v_exp_f32_e32 v217, v217
	v_exp_f32_e32 v218, v218
	v_exp_f32_e32 v219, v219
	s_waitcnt lgkmcnt(8)
	v_mfma_f32_32x32x16_bf16 v[48:63], v[206:209], v[244:247], v[48:63]
	ds_read_b64_tr_b16 v[244:245], v4 offset:56448
	ds_read_b64_tr_b16 v[246:247], v4 offset:59008
	v_exp_f32_e32 v220, v220
	v_exp_f32_e32 v221, v221
	v_add_f32_e32 v252, v252, v214
	v_add_f32_e32 v253, v253, v215
	v_add_f32_e32 v254, v254, v216
	s_waitcnt lgkmcnt(8)
	v_mfma_f32_32x32x16_bf16 v[32:47], v[206:209], v[248:251], v[32:47]
	ds_read_b64_tr_b16 v[248:249], v4 offset:56512
	ds_read_b64_tr_b16 v[250:251], v4 offset:59072
	v_add_f32_e32 v205, v205, v217
	v_add_f32_e32 v252, v252, v218
	v_add_f32_e32 v253, v253, v219
	v_add_f32_e32 v254, v254, v220
	v_add_f32_e32 v205, v205, v221
	s_waitcnt lgkmcnt(8)
	v_mfma_f32_32x32x16_bf16 v[16:31], v[206:209], v[8:11], v[16:31]
	ds_read_b64_tr_b16 v[8:9], v4 offset:61440
	ds_read_b64_tr_b16 v[10:11], v4 offset:64000
	v_cvt_pk_bf16_f32 v214, v214, v215
	v_cvt_pk_bf16_f32 v215, v216, v217
	v_cvt_pk_bf16_f32 v216, v218, v219
	v_cvt_pk_bf16_f32 v217, v220, v221
	s_nop 1
	s_waitcnt lgkmcnt(8)
	v_mfma_f32_32x32x16_bf16 v[64:79], v[214:217], v[12:15], v[64:79]
	ds_read_b64_tr_b16 v[12:13], v4 offset:61504
	ds_read_b64_tr_b16 v[14:15], v4 offset:64064
	v_exp_f32_e32 v222, v222
	v_exp_f32_e32 v223, v223
	v_exp_f32_e32 v224, v224
	v_exp_f32_e32 v225, v225
	v_exp_f32_e32 v226, v226
	v_exp_f32_e32 v227, v227
	s_waitcnt lgkmcnt(8)
	v_mfma_f32_32x32x16_bf16 v[48:63], v[214:217], v[238:241], v[48:63]
	ds_read_b64_tr_b16 v[238:239], v4 offset:61568
	ds_read_b64_tr_b16 v[240:241], v4 offset:64128
	v_exp_f32_e32 v228, v228
	v_exp_f32_e32 v229, v229
	v_add_f32_e32 v252, v252, v222
	v_add_f32_e32 v253, v253, v223
	v_add_f32_e32 v254, v254, v224
	s_waitcnt lgkmcnt(8)
	v_mfma_f32_32x32x16_bf16 v[32:47], v[214:217], v[244:247], v[32:47]
	ds_read_b64_tr_b16 v[244:245], v4 offset:61632
	ds_read_b64_tr_b16 v[246:247], v4 offset:64192
	v_add_f32_e32 v205, v205, v225
	v_add_f32_e32 v252, v252, v226
	v_add_f32_e32 v253, v253, v227
	v_add_f32_e32 v254, v254, v228
	v_add_f32_e32 v205, v205, v229
	s_waitcnt lgkmcnt(8)
	v_mfma_f32_32x32x16_bf16 v[16:31], v[214:217], v[248:251], v[16:31]
	ds_read_b64_tr_b16 v[248:249], v5 offset:15360
	ds_read_b64_tr_b16 v[250:251], v5 offset:17920
	v_cvt_pk_bf16_f32 v222, v222, v223
	v_cvt_pk_bf16_f32 v223, v224, v225
	v_cvt_pk_bf16_f32 v224, v226, v227
	v_cvt_pk_bf16_f32 v225, v228, v229
	s_nop 1
	s_waitcnt lgkmcnt(8)
	v_mfma_f32_32x32x16_bf16 v[64:79], v[222:225], v[8:11], v[64:79]
	ds_read_b64_tr_b16 v[8:9], v5 offset:15424
	ds_read_b64_tr_b16 v[10:11], v5 offset:17984
	v_exp_f32_e32 v230, v230
	v_exp_f32_e32 v231, v231
	v_exp_f32_e32 v232, v232
	v_exp_f32_e32 v233, v233
	v_exp_f32_e32 v234, v234
	v_exp_f32_e32 v235, v235
	s_waitcnt lgkmcnt(8)
	v_mfma_f32_32x32x16_bf16 v[48:63], v[222:225], v[12:15], v[48:63]
	ds_read_b64_tr_b16 v[12:13], v5 offset:15488
	ds_read_b64_tr_b16 v[14:15], v5 offset:18048
	v_exp_f32_e32 v236, v236
	v_exp_f32_e32 v237, v237
	v_add_f32_e32 v252, v252, v230
	v_add_f32_e32 v253, v253, v231
	v_add_f32_e32 v254, v254, v232
	s_waitcnt lgkmcnt(8)
	v_mfma_f32_32x32x16_bf16 v[32:47], v[222:225], v[238:241], v[32:47]
	ds_read_b64_tr_b16 v[238:239], v5 offset:15552
	ds_read_b64_tr_b16 v[240:241], v5 offset:18112
	v_add_f32_e32 v205, v205, v233
	v_add_f32_e32 v252, v252, v234
	v_add_f32_e32 v253, v253, v235
	v_add_f32_e32 v254, v254, v236
	v_add_f32_e32 v205, v205, v237
	s_waitcnt lgkmcnt(8)
	v_mfma_f32_32x32x16_bf16 v[16:31], v[222:225], v[244:247], v[16:31]
	v_cvt_pk_bf16_f32 v230, v230, v231
	v_cvt_pk_bf16_f32 v231, v232, v233
	v_cvt_pk_bf16_f32 v232, v234, v235
	v_cvt_pk_bf16_f32 v233, v236, v237
	s_nop 1
	s_waitcnt lgkmcnt(6)
	v_mfma_f32_32x32x16_bf16 v[64:79], v[230:233], v[248:251], v[64:79]
	v_add_f32_e32 v252, v252, v253
	s_waitcnt lgkmcnt(4)
	v_mfma_f32_32x32x16_bf16 v[48:63], v[230:233], v[8:11], v[48:63]
	v_add_f32_e32 v254, v254, v205
	s_waitcnt lgkmcnt(2)
	v_mfma_f32_32x32x16_bf16 v[32:47], v[230:233], v[12:15], v[32:47]
	v_add_f32_e32 v252, v252, v254
	s_waitcnt lgkmcnt(0)
	v_mfma_f32_32x32x16_bf16 v[16:31], v[230:233], v[238:241], v[16:31]
	v_add_f32_e32 v2, v2, v252
